# K-loop: saddr LDS-DMA + early post-MFMA barrier with prio raise + redundant wait/prio flips removed
# speedup vs baseline: 1.0087x; 1.0023x over previous
.LBB0_268:
	v_add_u32_e32 v160, s43, v1
	ds_read_b128 v[156:159], v160
	ds_read_b128 v[162:165], v160 offset:1024
	ds_read_b128 v[166:169], v160 offset:2048
	ds_read_b128 v[170:173], v160 offset:3072
	v_add_u32_e32 v160, s44, v1
	ds_read_b128 v[174:177], v160
	ds_read_b128 v[178:181], v160 offset:1024
	ds_read_b128 v[182:185], v160 offset:2048
	ds_read_b128 v[192:195], v160 offset:3072
	s_add_u32 s52, s30, 0x10000
	s_addc_u32 s53, s31, 0
	s_cmp_eq_u32 s67, 12
	s_cselect_b32 s64, s51, s52
	s_cselect_b32 s65, s50, s53
	s_cselect_b32 s62, s55, s61
	s_cselect_b32 s63, s54, s66
	s_add_u32 s56, s64, 0x8000
	s_addc_u32 s57, s65, 0
	s_add_i32 m0, s36, 0xc000
	ds_read_b128 v[200:203], v155
	ds_read_b128 v[204:207], v155 offset:1024
	ds_read_b128 v[208:211], v155 offset:2048
	ds_read_b128 v[212:215], v155 offset:3072
	ds_read_b128 v[216:219], v155 offset:4096
	ds_read_b128 v[220:223], v155 offset:5120
	ds_read_b128 v[224:227], v155 offset:6144
	ds_read_b128 v[228:231], v155 offset:7168
	global_load_lds_dwordx4 v146, s[30:31] sc1
	s_add_i32 m0, s36, 0xe000
	s_nop 0
	global_load_lds_dwordx4 v148, s[30:31] sc1
	s_waitcnt vmcnt(8)
	s_waitcnt lgkmcnt(0)
	s_setprio 1
	s_barrier
	v_mfma_f32_16x16x32_bf16 v[118:121], v[156:159], v[200:203], v[118:121]
	v_mfma_f32_16x16x32_bf16 v[110:113], v[166:169], v[200:203], v[110:113]
	v_mfma_f32_16x16x32_bf16 v[102:105], v[156:159], v[208:211], v[102:105]
	v_mfma_f32_16x16x32_bf16 v[94:97], v[166:169], v[208:211], v[94:97]
	v_mfma_f32_16x16x32_bf16 v[86:89], v[156:159], v[216:219], v[86:89]
	v_mfma_f32_16x16x32_bf16 v[78:81], v[166:169], v[216:219], v[78:81]
	v_mfma_f32_16x16x32_bf16 v[62:65], v[156:159], v[224:227], v[62:65]
	v_mfma_f32_16x16x32_bf16 v[54:57], v[166:169], v[224:227], v[54:57]
	v_mfma_f32_16x16x32_bf16 v[118:121], v[162:165], v[204:207], v[118:121]
	v_mfma_f32_16x16x32_bf16 v[110:113], v[170:173], v[204:207], v[110:113]
	v_mfma_f32_16x16x32_bf16 v[102:105], v[162:165], v[212:215], v[102:105]
	v_mfma_f32_16x16x32_bf16 v[94:97], v[170:173], v[212:215], v[94:97]
	v_mfma_f32_16x16x32_bf16 v[86:89], v[162:165], v[220:223], v[86:89]
	v_mfma_f32_16x16x32_bf16 v[78:81], v[170:173], v[220:223], v[78:81]
	v_mfma_f32_16x16x32_bf16 v[62:65], v[162:165], v[228:231], v[62:65]
	v_mfma_f32_16x16x32_bf16 v[54:57], v[170:173], v[228:231], v[54:57]
	v_mfma_f32_16x16x32_bf16 v[126:129], v[174:177], v[200:203], v[126:129]
	v_mfma_f32_16x16x32_bf16 v[122:125], v[182:185], v[200:203], v[122:125]
	v_mfma_f32_16x16x32_bf16 v[114:117], v[174:177], v[208:211], v[114:117]
	v_mfma_f32_16x16x32_bf16 v[106:109], v[182:185], v[208:211], v[106:109]
	v_mfma_f32_16x16x32_bf16 v[98:101], v[174:177], v[216:219], v[98:101]
	v_mfma_f32_16x16x32_bf16 v[90:93], v[182:185], v[216:219], v[90:93]
	v_mfma_f32_16x16x32_bf16 v[82:85], v[174:177], v[224:227], v[82:85]
	v_mfma_f32_16x16x32_bf16 v[70:73], v[182:185], v[224:227], v[70:73]
	v_mfma_f32_16x16x32_bf16 v[126:129], v[178:181], v[204:207], v[126:129]
	v_mfma_f32_16x16x32_bf16 v[122:125], v[192:195], v[204:207], v[122:125]
	v_mfma_f32_16x16x32_bf16 v[114:117], v[178:181], v[212:215], v[114:117]
	v_mfma_f32_16x16x32_bf16 v[106:109], v[192:195], v[212:215], v[106:109]
	v_mfma_f32_16x16x32_bf16 v[98:101], v[178:181], v[220:223], v[98:101]
	v_mfma_f32_16x16x32_bf16 v[90:93], v[192:195], v[220:223], v[90:93]
	s_setprio 2
	s_barrier
	v_mfma_f32_16x16x32_bf16 v[82:85], v[178:181], v[228:231], v[82:85]
	v_mfma_f32_16x16x32_bf16 v[70:73], v[192:195], v[228:231], v[70:73]
	s_setprio 0
	s_add_i32 s30, s43, s5
	s_mov_b32 m0, s30
	ds_read_b128 v[200:203], v155 offset:16384
	ds_read_b128 v[204:207], v155 offset:17408
	ds_read_b128 v[208:211], v155 offset:18432
	ds_read_b128 v[212:215], v155 offset:19456
	ds_read_b128 v[216:219], v155 offset:20480
	ds_read_b128 v[220:223], v155 offset:21504
	ds_read_b128 v[224:227], v155 offset:22528
	ds_read_b128 v[228:231], v155 offset:23552
	global_load_lds_dwordx4 v134, s[62:63] sc1
	s_add_i32 m0, s30, 0x2000
	s_add_u32 s30, s62, 0x4000
	s_addc_u32 s31, s63, 0
	s_add_i32 s69, s44, s5
	global_load_lds_dwordx4 v136, s[62:63] sc1
	s_mov_b32 m0, s69
	s_nop 0
	global_load_lds_dwordx4 v134, s[30:31] sc1
	s_add_i32 m0, s69, 0x2000
	s_nop 0
	global_load_lds_dwordx4 v136, s[30:31] sc1
	s_mov_b32 m0, s36
	s_nop 0
	global_load_lds_dwordx4 v132, s[64:65] sc1
	s_mov_b32 m0, s37
	s_nop 0
	global_load_lds_dwordx4 v130, s[64:65] sc1
	s_waitcnt vmcnt(8)
	s_waitcnt lgkmcnt(0)
	s_setprio 1
	s_barrier
	v_mfma_f32_16x16x32_bf16 v[58:61], v[156:159], v[200:203], v[58:61]
	v_mfma_f32_16x16x32_bf16 v[46:49], v[166:169], v[200:203], v[46:49]
	v_mfma_f32_16x16x32_bf16 v[38:41], v[156:159], v[208:211], v[38:41]
	v_mfma_f32_16x16x32_bf16 v[30:33], v[166:169], v[208:211], v[30:33]
	v_mfma_f32_16x16x32_bf16 v[22:25], v[156:159], v[216:219], v[22:25]
	v_mfma_f32_16x16x32_bf16 v[14:17], v[166:169], v[216:219], v[14:17]
	v_mfma_f32_16x16x32_bf16 v[6:9], v[156:159], v[224:227], v[6:9]
	v_mfma_f32_16x16x32_bf16 v[2:5], v[166:169], v[224:227], v[2:5]
	v_mfma_f32_16x16x32_bf16 v[58:61], v[162:165], v[204:207], v[58:61]
	v_mfma_f32_16x16x32_bf16 v[46:49], v[170:173], v[204:207], v[46:49]
	v_mfma_f32_16x16x32_bf16 v[38:41], v[162:165], v[212:215], v[38:41]
	v_mfma_f32_16x16x32_bf16 v[30:33], v[170:173], v[212:215], v[30:33]
	v_mfma_f32_16x16x32_bf16 v[22:25], v[162:165], v[220:223], v[22:25]
	v_mfma_f32_16x16x32_bf16 v[14:17], v[170:173], v[220:223], v[14:17]
	v_mfma_f32_16x16x32_bf16 v[6:9], v[162:165], v[228:231], v[6:9]
	v_mfma_f32_16x16x32_bf16 v[2:5], v[170:173], v[228:231], v[2:5]
	v_mfma_f32_16x16x32_bf16 v[74:77], v[174:177], v[200:203], v[74:77]
	v_mfma_f32_16x16x32_bf16 v[66:69], v[182:185], v[200:203], v[66:69]
	v_mfma_f32_16x16x32_bf16 v[50:53], v[174:177], v[208:211], v[50:53]
	v_mfma_f32_16x16x32_bf16 v[42:45], v[182:185], v[208:211], v[42:45]
	v_mfma_f32_16x16x32_bf16 v[34:37], v[174:177], v[216:219], v[34:37]
	v_mfma_f32_16x16x32_bf16 v[26:29], v[182:185], v[216:219], v[26:29]
	v_mfma_f32_16x16x32_bf16 v[18:21], v[174:177], v[224:227], v[18:21]
	v_mfma_f32_16x16x32_bf16 v[10:13], v[182:185], v[224:227], v[10:13]
	v_mfma_f32_16x16x32_bf16 v[74:77], v[178:181], v[204:207], v[74:77]
	v_mfma_f32_16x16x32_bf16 v[66:69], v[192:195], v[204:207], v[66:69]
	v_mfma_f32_16x16x32_bf16 v[50:53], v[178:181], v[212:215], v[50:53]
	v_mfma_f32_16x16x32_bf16 v[42:45], v[192:195], v[212:215], v[42:45]
	v_mfma_f32_16x16x32_bf16 v[34:37], v[178:181], v[220:223], v[34:37]
	v_mfma_f32_16x16x32_bf16 v[26:29], v[192:195], v[220:223], v[26:29]
	s_setprio 2
	s_barrier
	v_mfma_f32_16x16x32_bf16 v[18:21], v[178:181], v[228:231], v[18:21]
	v_mfma_f32_16x16x32_bf16 v[10:13], v[192:195], v[228:231], v[10:13]
	s_setprio 0
	v_add_u32_e32 v160, s45, v1
	ds_read_b128 v[156:159], v160
	ds_read_b128 v[162:165], v160 offset:1024
	ds_read_b128 v[166:169], v160 offset:2048
	ds_read_b128 v[170:173], v160 offset:3072
	v_add_u32_e32 v160, s46, v1
	ds_read_b128 v[174:177], v160
	ds_read_b128 v[178:181], v160 offset:1024
	ds_read_b128 v[182:185], v160 offset:2048
	ds_read_b128 v[192:195], v160 offset:3072
	s_add_u32 s30, s64, 0x4000
	s_addc_u32 s31, s65, 0
	s_mov_b32 m0, s38
	ds_read_b128 v[200:203], v155 offset:32768
	ds_read_b128 v[204:207], v155 offset:33792
	ds_read_b128 v[208:211], v155 offset:34816
	ds_read_b128 v[212:215], v155 offset:35840
	ds_read_b128 v[216:219], v155 offset:36864
	ds_read_b128 v[220:223], v155 offset:37888
	ds_read_b128 v[224:227], v155 offset:38912
	ds_read_b128 v[228:231], v155 offset:39936
	global_load_lds_dwordx4 v132, s[30:31] sc1
	s_mov_b32 m0, s39
	s_nop 0
	global_load_lds_dwordx4 v130, s[30:31] sc1
	s_waitcnt vmcnt(8)
	s_waitcnt lgkmcnt(0)
	s_setprio 1
	s_barrier
	v_mfma_f32_16x16x32_bf16 v[118:121], v[156:159], v[200:203], v[118:121]
	v_mfma_f32_16x16x32_bf16 v[110:113], v[166:169], v[200:203], v[110:113]
	v_mfma_f32_16x16x32_bf16 v[102:105], v[156:159], v[208:211], v[102:105]
	v_mfma_f32_16x16x32_bf16 v[94:97], v[166:169], v[208:211], v[94:97]
	v_mfma_f32_16x16x32_bf16 v[86:89], v[156:159], v[216:219], v[86:89]
	v_mfma_f32_16x16x32_bf16 v[78:81], v[166:169], v[216:219], v[78:81]
	v_mfma_f32_16x16x32_bf16 v[62:65], v[156:159], v[224:227], v[62:65]
	v_mfma_f32_16x16x32_bf16 v[54:57], v[166:169], v[224:227], v[54:57]
	v_mfma_f32_16x16x32_bf16 v[118:121], v[162:165], v[204:207], v[118:121]
	v_mfma_f32_16x16x32_bf16 v[110:113], v[170:173], v[204:207], v[110:113]
	v_mfma_f32_16x16x32_bf16 v[102:105], v[162:165], v[212:215], v[102:105]
	v_mfma_f32_16x16x32_bf16 v[94:97], v[170:173], v[212:215], v[94:97]
	v_mfma_f32_16x16x32_bf16 v[86:89], v[162:165], v[220:223], v[86:89]
	v_mfma_f32_16x16x32_bf16 v[78:81], v[170:173], v[220:223], v[78:81]
	v_mfma_f32_16x16x32_bf16 v[62:65], v[162:165], v[228:231], v[62:65]
	v_mfma_f32_16x16x32_bf16 v[54:57], v[170:173], v[228:231], v[54:57]
	v_mfma_f32_16x16x32_bf16 v[126:129], v[174:177], v[200:203], v[126:129]
	v_mfma_f32_16x16x32_bf16 v[122:125], v[182:185], v[200:203], v[122:125]
	v_mfma_f32_16x16x32_bf16 v[114:117], v[174:177], v[208:211], v[114:117]
	v_mfma_f32_16x16x32_bf16 v[106:109], v[182:185], v[208:211], v[106:109]
	v_mfma_f32_16x16x32_bf16 v[98:101], v[174:177], v[216:219], v[98:101]
	v_mfma_f32_16x16x32_bf16 v[90:93], v[182:185], v[216:219], v[90:93]
	v_mfma_f32_16x16x32_bf16 v[82:85], v[174:177], v[224:227], v[82:85]
	v_mfma_f32_16x16x32_bf16 v[70:73], v[182:185], v[224:227], v[70:73]
	v_mfma_f32_16x16x32_bf16 v[126:129], v[178:181], v[204:207], v[126:129]
	v_mfma_f32_16x16x32_bf16 v[122:125], v[192:195], v[204:207], v[122:125]
	v_mfma_f32_16x16x32_bf16 v[114:117], v[178:181], v[212:215], v[114:117]
	v_mfma_f32_16x16x32_bf16 v[106:109], v[192:195], v[212:215], v[106:109]
	v_mfma_f32_16x16x32_bf16 v[98:101], v[178:181], v[220:223], v[98:101]
	v_mfma_f32_16x16x32_bf16 v[90:93], v[192:195], v[220:223], v[90:93]
	s_setprio 2
	s_barrier
	v_mfma_f32_16x16x32_bf16 v[82:85], v[178:181], v[228:231], v[82:85]
	v_mfma_f32_16x16x32_bf16 v[70:73], v[192:195], v[228:231], v[70:73]
	s_setprio 0
	s_add_u32 s30, s62, 0x8000
	s_addc_u32 s31, s63, 0
	s_add_i32 s64, s45, s5
	s_mov_b32 m0, s64
	ds_read_b128 v[200:203], v155 offset:49152
	ds_read_b128 v[204:207], v155 offset:50176
	ds_read_b128 v[208:211], v155 offset:51200
	ds_read_b128 v[212:215], v155 offset:52224
	ds_read_b128 v[216:219], v155 offset:53248
	ds_read_b128 v[220:223], v155 offset:54272
	ds_read_b128 v[224:227], v155 offset:55296
	ds_read_b128 v[228:231], v155 offset:56320
	global_load_lds_dwordx4 v134, s[30:31] sc1
	s_add_i32 m0, s64, 0x2000
	s_nop 0
	global_load_lds_dwordx4 v136, s[30:31] sc1
	s_add_u32 s30, s62, 0xc000
	s_addc_u32 s31, s63, 0
	s_add_i32 s62, s46, s5
	s_mov_b32 m0, s62
	s_nop 0
	global_load_lds_dwordx4 v134, s[30:31] sc1
	s_add_i32 m0, s62, 0x2000
	s_nop 0
	global_load_lds_dwordx4 v136, s[30:31] sc1
	s_mov_b32 m0, s40
	s_nop 0
	global_load_lds_dwordx4 v132, s[56:57] sc1
	s_mov_b32 m0, s41
	s_nop 0
	global_load_lds_dwordx4 v130, s[56:57] sc1
	s_waitcnt vmcnt(8)
	s_waitcnt lgkmcnt(0)
	s_setprio 1
	s_barrier
	v_mfma_f32_16x16x32_bf16 v[58:61], v[156:159], v[200:203], v[58:61]
	v_mfma_f32_16x16x32_bf16 v[46:49], v[166:169], v[200:203], v[46:49]
	v_mfma_f32_16x16x32_bf16 v[38:41], v[156:159], v[208:211], v[38:41]
	v_mfma_f32_16x16x32_bf16 v[30:33], v[166:169], v[208:211], v[30:33]
	v_mfma_f32_16x16x32_bf16 v[22:25], v[156:159], v[216:219], v[22:25]
	v_mfma_f32_16x16x32_bf16 v[14:17], v[166:169], v[216:219], v[14:17]
	v_mfma_f32_16x16x32_bf16 v[6:9], v[156:159], v[224:227], v[6:9]
	v_mfma_f32_16x16x32_bf16 v[2:5], v[166:169], v[224:227], v[2:5]
	v_mfma_f32_16x16x32_bf16 v[58:61], v[162:165], v[204:207], v[58:61]
	v_mfma_f32_16x16x32_bf16 v[46:49], v[170:173], v[204:207], v[46:49]
	v_mfma_f32_16x16x32_bf16 v[38:41], v[162:165], v[212:215], v[38:41]
	v_mfma_f32_16x16x32_bf16 v[30:33], v[170:173], v[212:215], v[30:33]
	v_mfma_f32_16x16x32_bf16 v[22:25], v[162:165], v[220:223], v[22:25]
	v_mfma_f32_16x16x32_bf16 v[14:17], v[170:173], v[220:223], v[14:17]
	v_mfma_f32_16x16x32_bf16 v[6:9], v[162:165], v[228:231], v[6:9]
	v_mfma_f32_16x16x32_bf16 v[2:5], v[170:173], v[228:231], v[2:5]
	v_mfma_f32_16x16x32_bf16 v[74:77], v[174:177], v[200:203], v[74:77]
	v_mfma_f32_16x16x32_bf16 v[66:69], v[182:185], v[200:203], v[66:69]
	v_mfma_f32_16x16x32_bf16 v[50:53], v[174:177], v[208:211], v[50:53]
	v_mfma_f32_16x16x32_bf16 v[42:45], v[182:185], v[208:211], v[42:45]
	v_mfma_f32_16x16x32_bf16 v[34:37], v[174:177], v[216:219], v[34:37]
	v_mfma_f32_16x16x32_bf16 v[26:29], v[182:185], v[216:219], v[26:29]
	v_mfma_f32_16x16x32_bf16 v[18:21], v[174:177], v[224:227], v[18:21]
	v_mfma_f32_16x16x32_bf16 v[10:13], v[182:185], v[224:227], v[10:13]
	v_mfma_f32_16x16x32_bf16 v[74:77], v[178:181], v[204:207], v[74:77]
	v_mfma_f32_16x16x32_bf16 v[66:69], v[192:195], v[204:207], v[66:69]
	v_mfma_f32_16x16x32_bf16 v[50:53], v[178:181], v[212:215], v[50:53]
	v_mfma_f32_16x16x32_bf16 v[42:45], v[192:195], v[212:215], v[42:45]
	v_mfma_f32_16x16x32_bf16 v[34:37], v[178:181], v[220:223], v[34:37]
	v_mfma_f32_16x16x32_bf16 v[26:29], v[192:195], v[220:223], v[26:29]
	s_setprio 2
	s_barrier
	v_mfma_f32_16x16x32_bf16 v[18:21], v[178:181], v[228:231], v[18:21]
	v_mfma_f32_16x16x32_bf16 v[10:13], v[192:195], v[228:231], v[10:13]
	s_setprio 0
	s_add_i32 s67, s67, 2
	s_add_u32 s61, s61, 0x10000
	s_addc_u32 s66, s66, 0
	s_cmp_gt_u32 s67, 13
	s_mov_b64 s[30:31], s[52:53]
	s_cbranch_scc0 .LBB0_268
	s_and_b64 vcc, exec, s[10:11]
	s_cbranch_vccz .LBB0_271
	s_barrier

.LBB0_404:
	s_add_u32 s29, s30, s8
	v_add_u32_e32 v157, s45, v153
	s_addc_u32 s55, s31, s9
	ds_read_b128 v[162:165], v157
	ds_read_b128 v[166:169], v157 offset:1024
	ds_read_b128 v[170:173], v157 offset:2048
	ds_read_b128 v[174:177], v157 offset:3072
	v_add_u32_e32 v157, s47, v153
	s_add_u32 s29, s29, 0x10000
	ds_read_b128 v[178:181], v157
	ds_read_b128 v[182:185], v157 offset:1024
	ds_read_b128 v[192:195], v157 offset:2048
	ds_read_b128 v[200:203], v157 offset:3072
	s_addc_u32 s55, s55, 0
	s_add_u32 s62, s61, s8
	s_addc_u32 s63, s69, s9
	s_cmp_eq_u32 s8, 0x150000
	s_cselect_b32 s66, s71, s29
	s_cselect_b32 s67, s70, s55
	s_cselect_b32 s64, s79, s62
	s_cselect_b32 s65, s78, s63
	s_add_u32 s62, s66, 0x8000
	s_addc_u32 s63, s67, 0
	s_add_i32 s29, s37, 0xc000
	v_lshl_add_u64 v[158:159], v[146:147], 0, s[8:9]
	s_mov_b32 m0, s29
	s_add_i32 s55, s37, 0xe000
	ds_read_b128 v[204:207], v155
	ds_read_b128 v[208:211], v155 offset:1024
	ds_read_b128 v[212:215], v155 offset:2048
	ds_read_b128 v[216:219], v155 offset:3072
	ds_read_b128 v[220:223], v155 offset:4096
	ds_read_b128 v[224:227], v155 offset:5120
	ds_read_b128 v[228:231], v155 offset:6144
	ds_read_b128 v[232:235], v155 offset:7168
	global_load_lds_dwordx4 v[158:159], off sc1
	v_lshl_add_u64 v[158:159], v[148:149], 0, s[8:9]
	s_mov_b32 m0, s55
	s_nop 0
	global_load_lds_dwordx4 v[158:159], off sc1
	s_waitcnt vmcnt(8)
	s_waitcnt lgkmcnt(0)
	s_setprio 1
	s_barrier
	v_mfma_f32_16x16x32_bf16 v[114:117], v[162:165], v[204:207], v[114:117]
	v_mfma_f32_16x16x32_bf16 v[118:121], v[170:173], v[204:207], v[118:121]
	v_mfma_f32_16x16x32_bf16 v[98:101], v[162:165], v[212:215], v[98:101]
	v_mfma_f32_16x16x32_bf16 v[102:105], v[170:173], v[212:215], v[102:105]
	v_mfma_f32_16x16x32_bf16 v[82:85], v[162:165], v[220:223], v[82:85]
	v_mfma_f32_16x16x32_bf16 v[86:89], v[170:173], v[220:223], v[86:89]
	v_mfma_f32_16x16x32_bf16 v[66:69], v[162:165], v[228:231], v[66:69]
	v_mfma_f32_16x16x32_bf16 v[70:73], v[170:173], v[228:231], v[70:73]
	v_mfma_f32_16x16x32_bf16 v[114:117], v[166:169], v[208:211], v[114:117]
	v_mfma_f32_16x16x32_bf16 v[118:121], v[174:177], v[208:211], v[118:121]
	v_mfma_f32_16x16x32_bf16 v[98:101], v[166:169], v[216:219], v[98:101]
	v_mfma_f32_16x16x32_bf16 v[102:105], v[174:177], v[216:219], v[102:105]
	v_mfma_f32_16x16x32_bf16 v[82:85], v[166:169], v[224:227], v[82:85]
	v_mfma_f32_16x16x32_bf16 v[86:89], v[174:177], v[224:227], v[86:89]
	v_mfma_f32_16x16x32_bf16 v[66:69], v[166:169], v[232:235], v[66:69]
	v_mfma_f32_16x16x32_bf16 v[70:73], v[174:177], v[232:235], v[70:73]
	v_mfma_f32_16x16x32_bf16 v[122:125], v[178:181], v[204:207], v[122:125]
	v_mfma_f32_16x16x32_bf16 v[126:129], v[192:195], v[204:207], v[126:129]
	v_mfma_f32_16x16x32_bf16 v[106:109], v[178:181], v[212:215], v[106:109]
	v_mfma_f32_16x16x32_bf16 v[110:113], v[192:195], v[212:215], v[110:113]
	v_mfma_f32_16x16x32_bf16 v[90:93], v[178:181], v[220:223], v[90:93]
	v_mfma_f32_16x16x32_bf16 v[94:97], v[192:195], v[220:223], v[94:97]
	v_mfma_f32_16x16x32_bf16 v[74:77], v[178:181], v[228:231], v[74:77]
	v_mfma_f32_16x16x32_bf16 v[78:81], v[192:195], v[228:231], v[78:81]
	v_mfma_f32_16x16x32_bf16 v[122:125], v[182:185], v[208:211], v[122:125]
	v_mfma_f32_16x16x32_bf16 v[126:129], v[200:203], v[208:211], v[126:129]
	v_mfma_f32_16x16x32_bf16 v[106:109], v[182:185], v[216:219], v[106:109]
	v_mfma_f32_16x16x32_bf16 v[110:113], v[200:203], v[216:219], v[110:113]
	v_mfma_f32_16x16x32_bf16 v[90:93], v[182:185], v[224:227], v[90:93]
	v_mfma_f32_16x16x32_bf16 v[94:97], v[200:203], v[224:227], v[94:97]
	s_setprio 2
	s_barrier
	v_mfma_f32_16x16x32_bf16 v[74:77], v[182:185], v[232:235], v[74:77]
	v_mfma_f32_16x16x32_bf16 v[78:81], v[200:203], v[232:235], v[78:81]
	s_setprio 0
	s_add_i32 s81, s45, s35
	s_mov_b32 m0, s81
	ds_read_b128 v[204:207], v155 offset:16384
	ds_read_b128 v[208:211], v155 offset:17408
	ds_read_b128 v[212:215], v155 offset:18432
	ds_read_b128 v[216:219], v155 offset:19456
	ds_read_b128 v[220:223], v155 offset:20480
	ds_read_b128 v[224:227], v155 offset:21504
	ds_read_b128 v[228:231], v155 offset:22528
	ds_read_b128 v[232:235], v155 offset:23552
	global_load_lds_dwordx4 v132, s[64:65] sc1
	s_add_i32 m0, s81, 0x2000
	s_add_u32 s82, s64, 0x4000
	s_addc_u32 s83, s65, 0
	s_add_i32 s81, s47, s35
	global_load_lds_dwordx4 v136, s[64:65] sc1
	s_mov_b32 m0, s81
	s_nop 0
	global_load_lds_dwordx4 v132, s[82:83] sc1
	s_add_i32 m0, s81, 0x2000
	s_nop 0
	global_load_lds_dwordx4 v136, s[82:83] sc1
	s_mov_b32 m0, s37
	s_nop 0
	global_load_lds_dwordx4 v130, s[66:67] sc1
	s_mov_b32 m0, s39
	s_nop 0
	global_load_lds_dwordx4 v134, s[66:67] sc1
	s_waitcnt vmcnt(8)
	s_waitcnt lgkmcnt(0)
	s_setprio 1
	s_barrier
	v_mfma_f32_16x16x32_bf16 v[50:53], v[162:165], v[204:207], v[50:53]
	v_mfma_f32_16x16x32_bf16 v[54:57], v[170:173], v[204:207], v[54:57]
	v_mfma_f32_16x16x32_bf16 v[34:37], v[162:165], v[212:215], v[34:37]
	v_mfma_f32_16x16x32_bf16 v[38:41], v[170:173], v[212:215], v[38:41]
	v_mfma_f32_16x16x32_bf16 v[18:21], v[162:165], v[220:223], v[18:21]
	v_mfma_f32_16x16x32_bf16 v[22:25], v[170:173], v[220:223], v[22:25]
	v_mfma_f32_16x16x32_bf16 v[2:5], v[162:165], v[228:231], v[2:5]
	v_mfma_f32_16x16x32_bf16 v[6:9], v[170:173], v[228:231], v[6:9]
	v_mfma_f32_16x16x32_bf16 v[50:53], v[166:169], v[208:211], v[50:53]
	v_mfma_f32_16x16x32_bf16 v[54:57], v[174:177], v[208:211], v[54:57]
	v_mfma_f32_16x16x32_bf16 v[34:37], v[166:169], v[216:219], v[34:37]
	v_mfma_f32_16x16x32_bf16 v[38:41], v[174:177], v[216:219], v[38:41]
	v_mfma_f32_16x16x32_bf16 v[18:21], v[166:169], v[224:227], v[18:21]
	v_mfma_f32_16x16x32_bf16 v[22:25], v[174:177], v[224:227], v[22:25]
	v_mfma_f32_16x16x32_bf16 v[2:5], v[166:169], v[232:235], v[2:5]
	v_mfma_f32_16x16x32_bf16 v[6:9], v[174:177], v[232:235], v[6:9]
	v_mfma_f32_16x16x32_bf16 v[58:61], v[178:181], v[204:207], v[58:61]
	v_mfma_f32_16x16x32_bf16 v[62:65], v[192:195], v[204:207], v[62:65]
	v_mfma_f32_16x16x32_bf16 v[42:45], v[178:181], v[212:215], v[42:45]
	v_mfma_f32_16x16x32_bf16 v[46:49], v[192:195], v[212:215], v[46:49]
	v_mfma_f32_16x16x32_bf16 v[26:29], v[178:181], v[220:223], v[26:29]
	v_mfma_f32_16x16x32_bf16 v[30:33], v[192:195], v[220:223], v[30:33]
	v_mfma_f32_16x16x32_bf16 v[10:13], v[178:181], v[228:231], v[10:13]
	v_mfma_f32_16x16x32_bf16 v[14:17], v[192:195], v[228:231], v[14:17]
	v_mfma_f32_16x16x32_bf16 v[58:61], v[182:185], v[208:211], v[58:61]
	v_mfma_f32_16x16x32_bf16 v[62:65], v[200:203], v[208:211], v[62:65]
	v_mfma_f32_16x16x32_bf16 v[42:45], v[182:185], v[216:219], v[42:45]
	v_mfma_f32_16x16x32_bf16 v[46:49], v[200:203], v[216:219], v[46:49]
	v_mfma_f32_16x16x32_bf16 v[26:29], v[182:185], v[224:227], v[26:29]
	v_mfma_f32_16x16x32_bf16 v[30:33], v[200:203], v[224:227], v[30:33]
	s_setprio 2
	s_barrier
	v_mfma_f32_16x16x32_bf16 v[10:13], v[182:185], v[232:235], v[10:13]
	v_mfma_f32_16x16x32_bf16 v[14:17], v[200:203], v[232:235], v[14:17]
	s_setprio 0
	v_add_u32_e32 v157, s48, v153
	ds_read_b128 v[162:165], v157
	ds_read_b128 v[166:169], v157 offset:1024
	ds_read_b128 v[170:173], v157 offset:2048
	ds_read_b128 v[174:177], v157 offset:3072
	v_add_u32_e32 v157, s49, v153
	ds_read_b128 v[178:181], v157
	ds_read_b128 v[182:185], v157 offset:1024
	ds_read_b128 v[192:195], v157 offset:2048
	ds_read_b128 v[200:203], v157 offset:3072
	s_add_u32 s66, s66, 0x4000
	s_addc_u32 s67, s67, 0
	s_mov_b32 m0, s40
	ds_read_b128 v[204:207], v155 offset:32768
	ds_read_b128 v[208:211], v155 offset:33792
	ds_read_b128 v[212:215], v155 offset:34816
	ds_read_b128 v[216:219], v155 offset:35840
	ds_read_b128 v[220:223], v155 offset:36864
	ds_read_b128 v[224:227], v155 offset:37888
	ds_read_b128 v[228:231], v155 offset:38912
	ds_read_b128 v[232:235], v155 offset:39936
	global_load_lds_dwordx4 v130, s[66:67] sc1
	s_mov_b32 m0, s41
	s_nop 0
	global_load_lds_dwordx4 v134, s[66:67] sc1
	s_waitcnt vmcnt(8)
	s_waitcnt lgkmcnt(0)
	s_setprio 1
	s_barrier
	v_mfma_f32_16x16x32_bf16 v[114:117], v[162:165], v[204:207], v[114:117]
	v_mfma_f32_16x16x32_bf16 v[118:121], v[170:173], v[204:207], v[118:121]
	v_mfma_f32_16x16x32_bf16 v[98:101], v[162:165], v[212:215], v[98:101]
	v_mfma_f32_16x16x32_bf16 v[102:105], v[170:173], v[212:215], v[102:105]
	v_mfma_f32_16x16x32_bf16 v[82:85], v[162:165], v[220:223], v[82:85]
	v_mfma_f32_16x16x32_bf16 v[86:89], v[170:173], v[220:223], v[86:89]
	v_mfma_f32_16x16x32_bf16 v[66:69], v[162:165], v[228:231], v[66:69]
	v_mfma_f32_16x16x32_bf16 v[70:73], v[170:173], v[228:231], v[70:73]
	v_mfma_f32_16x16x32_bf16 v[114:117], v[166:169], v[208:211], v[114:117]
	v_mfma_f32_16x16x32_bf16 v[118:121], v[174:177], v[208:211], v[118:121]
	v_mfma_f32_16x16x32_bf16 v[98:101], v[166:169], v[216:219], v[98:101]
	v_mfma_f32_16x16x32_bf16 v[102:105], v[174:177], v[216:219], v[102:105]
	v_mfma_f32_16x16x32_bf16 v[82:85], v[166:169], v[224:227], v[82:85]
	v_mfma_f32_16x16x32_bf16 v[86:89], v[174:177], v[224:227], v[86:89]
	v_mfma_f32_16x16x32_bf16 v[66:69], v[166:169], v[232:235], v[66:69]
	v_mfma_f32_16x16x32_bf16 v[70:73], v[174:177], v[232:235], v[70:73]
	v_mfma_f32_16x16x32_bf16 v[122:125], v[178:181], v[204:207], v[122:125]
	v_mfma_f32_16x16x32_bf16 v[126:129], v[192:195], v[204:207], v[126:129]
	v_mfma_f32_16x16x32_bf16 v[106:109], v[178:181], v[212:215], v[106:109]
	v_mfma_f32_16x16x32_bf16 v[110:113], v[192:195], v[212:215], v[110:113]
	v_mfma_f32_16x16x32_bf16 v[90:93], v[178:181], v[220:223], v[90:93]
	v_mfma_f32_16x16x32_bf16 v[94:97], v[192:195], v[220:223], v[94:97]
	v_mfma_f32_16x16x32_bf16 v[74:77], v[178:181], v[228:231], v[74:77]
	v_mfma_f32_16x16x32_bf16 v[78:81], v[192:195], v[228:231], v[78:81]
	v_mfma_f32_16x16x32_bf16 v[122:125], v[182:185], v[208:211], v[122:125]
	v_mfma_f32_16x16x32_bf16 v[126:129], v[200:203], v[208:211], v[126:129]
	v_mfma_f32_16x16x32_bf16 v[106:109], v[182:185], v[216:219], v[106:109]
	v_mfma_f32_16x16x32_bf16 v[110:113], v[200:203], v[216:219], v[110:113]
	v_mfma_f32_16x16x32_bf16 v[90:93], v[182:185], v[224:227], v[90:93]
	v_mfma_f32_16x16x32_bf16 v[94:97], v[200:203], v[224:227], v[94:97]
	s_setprio 2
	s_barrier
	v_mfma_f32_16x16x32_bf16 v[74:77], v[182:185], v[232:235], v[74:77]
	v_mfma_f32_16x16x32_bf16 v[78:81], v[200:203], v[232:235], v[78:81]
	s_setprio 0
	s_add_u32 s66, s64, 0x8000
	s_addc_u32 s67, s65, 0
	s_add_i32 s81, s48, s35
	s_mov_b32 m0, s81
	ds_read_b128 v[204:207], v155 offset:49152
	ds_read_b128 v[208:211], v155 offset:50176
	ds_read_b128 v[212:215], v155 offset:51200
	ds_read_b128 v[216:219], v155 offset:52224
	ds_read_b128 v[220:223], v155 offset:53248
	ds_read_b128 v[224:227], v155 offset:54272
	ds_read_b128 v[228:231], v155 offset:55296
	ds_read_b128 v[232:235], v155 offset:56320
	global_load_lds_dwordx4 v132, s[66:67] sc1
	s_add_i32 m0, s81, 0x2000
	s_add_u32 s64, s64, 0xc000
	global_load_lds_dwordx4 v136, s[66:67] sc1
	s_addc_u32 s65, s65, 0
	s_add_i32 s66, s49, s35
	s_mov_b32 m0, s66
	s_nop 0
	global_load_lds_dwordx4 v132, s[64:65] sc1
	s_add_i32 m0, s66, 0x2000
	s_nop 0
	global_load_lds_dwordx4 v136, s[64:65] sc1
	s_mov_b32 m0, s43
	s_nop 0
	global_load_lds_dwordx4 v130, s[62:63] sc1
	s_mov_b32 m0, s44
	s_nop 0
	global_load_lds_dwordx4 v134, s[62:63] sc1
	s_waitcnt vmcnt(8)
	s_waitcnt lgkmcnt(0)
	s_setprio 1
	s_barrier
	v_mfma_f32_16x16x32_bf16 v[50:53], v[162:165], v[204:207], v[50:53]
	v_mfma_f32_16x16x32_bf16 v[54:57], v[170:173], v[204:207], v[54:57]
	v_mfma_f32_16x16x32_bf16 v[34:37], v[162:165], v[212:215], v[34:37]
	v_mfma_f32_16x16x32_bf16 v[38:41], v[170:173], v[212:215], v[38:41]
	v_mfma_f32_16x16x32_bf16 v[18:21], v[162:165], v[220:223], v[18:21]
	v_mfma_f32_16x16x32_bf16 v[22:25], v[170:173], v[220:223], v[22:25]
	v_mfma_f32_16x16x32_bf16 v[2:5], v[162:165], v[228:231], v[2:5]
	v_mfma_f32_16x16x32_bf16 v[6:9], v[170:173], v[228:231], v[6:9]
	v_mfma_f32_16x16x32_bf16 v[50:53], v[166:169], v[208:211], v[50:53]
	v_mfma_f32_16x16x32_bf16 v[54:57], v[174:177], v[208:211], v[54:57]
	v_mfma_f32_16x16x32_bf16 v[34:37], v[166:169], v[216:219], v[34:37]
	v_mfma_f32_16x16x32_bf16 v[38:41], v[174:177], v[216:219], v[38:41]
	v_mfma_f32_16x16x32_bf16 v[18:21], v[166:169], v[224:227], v[18:21]
	v_mfma_f32_16x16x32_bf16 v[22:25], v[174:177], v[224:227], v[22:25]
	v_mfma_f32_16x16x32_bf16 v[2:5], v[166:169], v[232:235], v[2:5]
	v_mfma_f32_16x16x32_bf16 v[6:9], v[174:177], v[232:235], v[6:9]
	v_mfma_f32_16x16x32_bf16 v[58:61], v[178:181], v[204:207], v[58:61]
	v_mfma_f32_16x16x32_bf16 v[62:65], v[192:195], v[204:207], v[62:65]
	v_mfma_f32_16x16x32_bf16 v[42:45], v[178:181], v[212:215], v[42:45]
	v_mfma_f32_16x16x32_bf16 v[46:49], v[192:195], v[212:215], v[46:49]
	v_mfma_f32_16x16x32_bf16 v[26:29], v[178:181], v[220:223], v[26:29]
	v_mfma_f32_16x16x32_bf16 v[30:33], v[192:195], v[220:223], v[30:33]
	v_mfma_f32_16x16x32_bf16 v[10:13], v[178:181], v[228:231], v[10:13]
	v_mfma_f32_16x16x32_bf16 v[14:17], v[192:195], v[228:231], v[14:17]
	v_mfma_f32_16x16x32_bf16 v[58:61], v[182:185], v[208:211], v[58:61]
	v_mfma_f32_16x16x32_bf16 v[62:65], v[200:203], v[208:211], v[62:65]
	v_mfma_f32_16x16x32_bf16 v[42:45], v[182:185], v[216:219], v[42:45]
	v_mfma_f32_16x16x32_bf16 v[46:49], v[200:203], v[216:219], v[46:49]
	v_mfma_f32_16x16x32_bf16 v[26:29], v[182:185], v[224:227], v[26:29]
	v_mfma_f32_16x16x32_bf16 v[30:33], v[200:203], v[224:227], v[30:33]
	s_setprio 2
	s_barrier
	v_mfma_f32_16x16x32_bf16 v[10:13], v[182:185], v[232:235], v[10:13]
	v_mfma_f32_16x16x32_bf16 v[14:17], v[200:203], v[232:235], v[14:17]
	s_setprio 0
	s_add_i32 s80, s80, 2
	s_add_u32 s8, s8, 0x10000
	s_addc_u32 s9, s9, 0
	s_cmp_gt_u32 s80, 41
	s_cbranch_scc0 .LBB0_404
	s_add_u32 s8, s61, 0xffff0000
	s_addc_u32 s9, s69, -1
	s_and_b64 vcc, exec, s[6:7]
	s_cbranch_vccnz .LBB0_391
	s_mov_b32 s10, s50
	s_mov_b32 s28, s51
	s_mov_b64 s[30:31], s[56:57]
	s_mov_b32 s46, s54
	v_mov_b64 v[114:115], 0
	v_mov_b64 v[116:117], 0
	v_mov_b64 v[118:119], 0
	v_mov_b64 v[120:121], 0
	v_mov_b64 v[98:99], 0
	v_mov_b64 v[100:101], 0
	v_mov_b64 v[102:103], 0
	v_mov_b64 v[104:105], 0
	v_mov_b64 v[82:83], 0
	v_mov_b64 v[84:85], 0
	v_mov_b64 v[86:87], 0
	v_mov_b64 v[88:89], 0
	v_mov_b64 v[66:67], 0
	v_mov_b64 v[68:69], 0
	v_mov_b64 v[70:71], 0
	v_mov_b64 v[72:73], 0
	v_mov_b64 v[122:123], 0
	v_mov_b64 v[124:125], 0
	v_mov_b64 v[126:127], 0
	v_mov_b64 v[128:129], 0
	v_mov_b64 v[106:107], 0
	v_mov_b64 v[108:109], 0
	v_mov_b64 v[110:111], 0
	v_mov_b64 v[112:113], 0
	v_mov_b64 v[90:91], 0
	v_mov_b64 v[92:93], 0
	v_mov_b64 v[94:95], 0
	v_mov_b64 v[96:97], 0
	v_mov_b64 v[74:75], 0
	v_mov_b64 v[76:77], 0
	v_mov_b64 v[78:79], 0
	v_mov_b64 v[80:81], 0
	v_mov_b64 v[50:51], 0
	v_mov_b64 v[52:53], 0
	v_mov_b64 v[54:55], 0
	v_mov_b64 v[56:57], 0
	v_mov_b64 v[34:35], 0
	v_mov_b64 v[36:37], 0
	v_mov_b64 v[38:39], 0
	v_mov_b64 v[40:41], 0
	v_mov_b64 v[18:19], 0
	v_mov_b64 v[20:21], 0
	v_mov_b64 v[22:23], 0
	v_mov_b64 v[24:25], 0
	v_mov_b64 v[2:3], 0
	v_mov_b64 v[4:5], 0
	v_mov_b64 v[6:7], 0
	v_mov_b64 v[8:9], 0
	v_mov_b64 v[58:59], 0
	v_mov_b64 v[60:61], 0
	v_mov_b64 v[62:63], 0
	v_mov_b64 v[64:65], 0
	v_mov_b64 v[42:43], 0
	v_mov_b64 v[44:45], 0
	v_mov_b64 v[46:47], 0
	v_mov_b64 v[48:49], 0
	v_mov_b64 v[26:27], 0
	v_mov_b64 v[28:29], 0
	v_mov_b64 v[30:31], 0
	v_mov_b64 v[32:33], 0
	v_mov_b64 v[10:11], 0
	v_mov_b64 v[12:13], 0
	v_mov_b64 v[14:15], 0
	v_mov_b64 v[16:17], 0
	s_andn2_b64 vcc, exec, s[4:5]
	s_cbranch_vccnz .LBB0_392

.LBB0_460:
	v_add_u32_e32 v134, s95, v1
	ds_read_b128 v[130:133], v134
	ds_read_b128 v[136:139], v134 offset:1024
	ds_read_b128 v[140:143], v134 offset:2048
	ds_read_b128 v[144:147], v134 offset:3072
	v_add_u32_e32 v134, s93, v1
	ds_read_b128 v[170:173], v134
	ds_read_b128 v[200:203], v134 offset:1024
	ds_read_b128 v[204:207], v134 offset:2048
	ds_read_b128 v[208:211], v134 offset:3072
	s_add_u32 s8, s4, 0x10000
	s_addc_u32 s9, s5, 0
	s_cmp_eq_u32 s46, 12
	s_cselect_b32 s84, s41, s8
	s_cselect_b32 s85, s35, s9
	s_cselect_b32 s64, s43, s44
	s_cselect_b32 s65, s42, s45
	s_add_u32 s56, s84, 0x8000
	s_addc_u32 s57, s85, 0
	s_add_i32 m0, s69, 0xc000
	ds_read_b128 v[212:215], v194
	ds_read_b128 v[216:219], v194 offset:1024
	ds_read_b128 v[220:223], v194 offset:2048
	ds_read_b128 v[224:227], v194 offset:3072
	ds_read_b128 v[228:231], v194 offset:4096
	ds_read_b128 v[232:235], v194 offset:5120
	ds_read_b128 v[236:239], v194 offset:6144
	ds_read_b128 v[240:243], v194 offset:7168
	global_load_lds_dwordx4 v166, s[4:5] sc1
	s_add_i32 m0, s69, 0xe000
	s_nop 0
	global_load_lds_dwordx4 v168, s[4:5] sc1
	s_waitcnt vmcnt(8)
	s_waitcnt lgkmcnt(0)
	s_setprio 1
	s_barrier
	v_mfma_f32_16x16x32_bf16 v[122:125], v[130:133], v[212:215], v[122:125]
	v_mfma_f32_16x16x32_bf16 v[126:129], v[140:143], v[212:215], v[126:129]
	v_mfma_f32_16x16x32_bf16 v[106:109], v[130:133], v[220:223], v[106:109]
	v_mfma_f32_16x16x32_bf16 v[110:113], v[140:143], v[220:223], v[110:113]
	v_mfma_f32_16x16x32_bf16 v[90:93], v[130:133], v[228:231], v[90:93]
	v_mfma_f32_16x16x32_bf16 v[94:97], v[140:143], v[228:231], v[94:97]
	v_mfma_f32_16x16x32_bf16 v[74:77], v[130:133], v[236:239], v[74:77]
	v_mfma_f32_16x16x32_bf16 v[78:81], v[140:143], v[236:239], v[78:81]
	v_mfma_f32_16x16x32_bf16 v[122:125], v[136:139], v[216:219], v[122:125]
	v_mfma_f32_16x16x32_bf16 v[126:129], v[144:147], v[216:219], v[126:129]
	v_mfma_f32_16x16x32_bf16 v[106:109], v[136:139], v[224:227], v[106:109]
	v_mfma_f32_16x16x32_bf16 v[110:113], v[144:147], v[224:227], v[110:113]
	v_mfma_f32_16x16x32_bf16 v[90:93], v[136:139], v[232:235], v[90:93]
	v_mfma_f32_16x16x32_bf16 v[94:97], v[144:147], v[232:235], v[94:97]
	v_mfma_f32_16x16x32_bf16 v[74:77], v[136:139], v[240:243], v[74:77]
	v_mfma_f32_16x16x32_bf16 v[78:81], v[144:147], v[240:243], v[78:81]
	v_mfma_f32_16x16x32_bf16 v[114:117], v[170:173], v[212:215], v[114:117]
	v_mfma_f32_16x16x32_bf16 v[118:121], v[204:207], v[212:215], v[118:121]
	v_mfma_f32_16x16x32_bf16 v[98:101], v[170:173], v[220:223], v[98:101]
	v_mfma_f32_16x16x32_bf16 v[102:105], v[204:207], v[220:223], v[102:105]
	v_mfma_f32_16x16x32_bf16 v[82:85], v[170:173], v[228:231], v[82:85]
	v_mfma_f32_16x16x32_bf16 v[86:89], v[204:207], v[228:231], v[86:89]
	v_mfma_f32_16x16x32_bf16 v[66:69], v[170:173], v[236:239], v[66:69]
	v_mfma_f32_16x16x32_bf16 v[70:73], v[204:207], v[236:239], v[70:73]
	v_mfma_f32_16x16x32_bf16 v[114:117], v[200:203], v[216:219], v[114:117]
	v_mfma_f32_16x16x32_bf16 v[118:121], v[208:211], v[216:219], v[118:121]
	v_mfma_f32_16x16x32_bf16 v[98:101], v[200:203], v[224:227], v[98:101]
	v_mfma_f32_16x16x32_bf16 v[102:105], v[208:211], v[224:227], v[102:105]
	v_mfma_f32_16x16x32_bf16 v[82:85], v[200:203], v[232:235], v[82:85]
	v_mfma_f32_16x16x32_bf16 v[86:89], v[208:211], v[232:235], v[86:89]
	s_setprio 2
	s_barrier
	v_mfma_f32_16x16x32_bf16 v[66:69], v[200:203], v[240:243], v[66:69]
	v_mfma_f32_16x16x32_bf16 v[70:73], v[208:211], v[240:243], v[70:73]
	s_setprio 0
	s_add_i32 s4, s95, s61
	s_mov_b32 m0, s4
	ds_read_b128 v[212:215], v194 offset:16384
	ds_read_b128 v[216:219], v194 offset:17408
	ds_read_b128 v[220:223], v194 offset:18432
	ds_read_b128 v[224:227], v194 offset:19456
	ds_read_b128 v[228:231], v194 offset:20480
	ds_read_b128 v[232:235], v194 offset:21504
	ds_read_b128 v[236:239], v194 offset:22528
	ds_read_b128 v[240:243], v194 offset:23552
	global_load_lds_dwordx4 v152, s[64:65] sc1
	s_add_i32 m0, s4, 0x2000
	s_add_u32 s4, s64, 0x4000
	s_addc_u32 s5, s65, 0
	s_add_i32 s47, s93, s61
	global_load_lds_dwordx4 v154, s[64:65] sc1
	s_mov_b32 m0, s47
	s_nop 0
	global_load_lds_dwordx4 v152, s[4:5] sc1
	s_add_i32 m0, s47, 0x2000
	s_nop 0
	global_load_lds_dwordx4 v154, s[4:5] sc1
	s_mov_b32 m0, s69
	s_nop 0
	global_load_lds_dwordx4 v150, s[84:85] sc1
	s_mov_b32 m0, s77
	s_nop 0
	global_load_lds_dwordx4 v148, s[84:85] sc1
	s_waitcnt vmcnt(8)
	s_waitcnt lgkmcnt(0)
	s_setprio 1
	s_barrier
	v_mfma_f32_16x16x32_bf16 v[58:61], v[130:133], v[212:215], v[58:61]
	v_mfma_f32_16x16x32_bf16 v[62:65], v[140:143], v[212:215], v[62:65]
	v_mfma_f32_16x16x32_bf16 v[42:45], v[130:133], v[220:223], v[42:45]
	v_mfma_f32_16x16x32_bf16 v[46:49], v[140:143], v[220:223], v[46:49]
	v_mfma_f32_16x16x32_bf16 v[26:29], v[130:133], v[228:231], v[26:29]
	v_mfma_f32_16x16x32_bf16 v[30:33], v[140:143], v[228:231], v[30:33]
	v_mfma_f32_16x16x32_bf16 v[10:13], v[130:133], v[236:239], v[10:13]
	v_mfma_f32_16x16x32_bf16 v[14:17], v[140:143], v[236:239], v[14:17]
	v_mfma_f32_16x16x32_bf16 v[58:61], v[136:139], v[216:219], v[58:61]
	v_mfma_f32_16x16x32_bf16 v[62:65], v[144:147], v[216:219], v[62:65]
	v_mfma_f32_16x16x32_bf16 v[42:45], v[136:139], v[224:227], v[42:45]
	v_mfma_f32_16x16x32_bf16 v[46:49], v[144:147], v[224:227], v[46:49]
	v_mfma_f32_16x16x32_bf16 v[26:29], v[136:139], v[232:235], v[26:29]
	v_mfma_f32_16x16x32_bf16 v[30:33], v[144:147], v[232:235], v[30:33]
	v_mfma_f32_16x16x32_bf16 v[10:13], v[136:139], v[240:243], v[10:13]
	v_mfma_f32_16x16x32_bf16 v[14:17], v[144:147], v[240:243], v[14:17]
	v_mfma_f32_16x16x32_bf16 v[50:53], v[170:173], v[212:215], v[50:53]
	v_mfma_f32_16x16x32_bf16 v[54:57], v[204:207], v[212:215], v[54:57]
	v_mfma_f32_16x16x32_bf16 v[34:37], v[170:173], v[220:223], v[34:37]
	v_mfma_f32_16x16x32_bf16 v[38:41], v[204:207], v[220:223], v[38:41]
	v_mfma_f32_16x16x32_bf16 v[18:21], v[170:173], v[228:231], v[18:21]
	v_mfma_f32_16x16x32_bf16 v[22:25], v[204:207], v[228:231], v[22:25]
	v_mfma_f32_16x16x32_bf16 v[2:5], v[170:173], v[236:239], v[2:5]
	v_mfma_f32_16x16x32_bf16 v[6:9], v[204:207], v[236:239], v[6:9]
	v_mfma_f32_16x16x32_bf16 v[50:53], v[200:203], v[216:219], v[50:53]
	v_mfma_f32_16x16x32_bf16 v[54:57], v[208:211], v[216:219], v[54:57]
	v_mfma_f32_16x16x32_bf16 v[34:37], v[200:203], v[224:227], v[34:37]
	v_mfma_f32_16x16x32_bf16 v[38:41], v[208:211], v[224:227], v[38:41]
	v_mfma_f32_16x16x32_bf16 v[18:21], v[200:203], v[232:235], v[18:21]
	v_mfma_f32_16x16x32_bf16 v[22:25], v[208:211], v[232:235], v[22:25]
	s_setprio 2
	s_barrier
	v_mfma_f32_16x16x32_bf16 v[2:5], v[200:203], v[240:243], v[2:5]
	v_mfma_f32_16x16x32_bf16 v[6:9], v[208:211], v[240:243], v[6:9]
	s_setprio 0
	v_add_u32_e32 v134, s36, v1
	ds_read_b128 v[130:133], v134
	ds_read_b128 v[136:139], v134 offset:1024
	ds_read_b128 v[140:143], v134 offset:2048
	ds_read_b128 v[144:147], v134 offset:3072
	v_add_u32_e32 v134, s37, v1
	ds_read_b128 v[170:173], v134
	ds_read_b128 v[200:203], v134 offset:1024
	ds_read_b128 v[204:207], v134 offset:2048
	ds_read_b128 v[208:211], v134 offset:3072
	s_add_u32 s4, s84, 0x4000
	s_addc_u32 s5, s85, 0
	s_mov_b32 m0, s86
	ds_read_b128 v[212:215], v194 offset:32768
	ds_read_b128 v[216:219], v194 offset:33792
	ds_read_b128 v[220:223], v194 offset:34816
	ds_read_b128 v[224:227], v194 offset:35840
	ds_read_b128 v[228:231], v194 offset:36864
	ds_read_b128 v[232:235], v194 offset:37888
	ds_read_b128 v[236:239], v194 offset:38912
	ds_read_b128 v[240:243], v194 offset:39936
	global_load_lds_dwordx4 v150, s[4:5] sc1
	s_mov_b32 m0, s87
	s_nop 0
	global_load_lds_dwordx4 v148, s[4:5] sc1
	s_waitcnt vmcnt(8)
	s_waitcnt lgkmcnt(0)
	s_setprio 1
	s_barrier
	v_mfma_f32_16x16x32_bf16 v[122:125], v[130:133], v[212:215], v[122:125]
	v_mfma_f32_16x16x32_bf16 v[126:129], v[140:143], v[212:215], v[126:129]
	v_mfma_f32_16x16x32_bf16 v[106:109], v[130:133], v[220:223], v[106:109]
	v_mfma_f32_16x16x32_bf16 v[110:113], v[140:143], v[220:223], v[110:113]
	v_mfma_f32_16x16x32_bf16 v[90:93], v[130:133], v[228:231], v[90:93]
	v_mfma_f32_16x16x32_bf16 v[94:97], v[140:143], v[228:231], v[94:97]
	v_mfma_f32_16x16x32_bf16 v[74:77], v[130:133], v[236:239], v[74:77]
	v_mfma_f32_16x16x32_bf16 v[78:81], v[140:143], v[236:239], v[78:81]
	v_mfma_f32_16x16x32_bf16 v[122:125], v[136:139], v[216:219], v[122:125]
	v_mfma_f32_16x16x32_bf16 v[126:129], v[144:147], v[216:219], v[126:129]
	v_mfma_f32_16x16x32_bf16 v[106:109], v[136:139], v[224:227], v[106:109]
	v_mfma_f32_16x16x32_bf16 v[110:113], v[144:147], v[224:227], v[110:113]
	v_mfma_f32_16x16x32_bf16 v[90:93], v[136:139], v[232:235], v[90:93]
	v_mfma_f32_16x16x32_bf16 v[94:97], v[144:147], v[232:235], v[94:97]
	v_mfma_f32_16x16x32_bf16 v[74:77], v[136:139], v[240:243], v[74:77]
	v_mfma_f32_16x16x32_bf16 v[78:81], v[144:147], v[240:243], v[78:81]
	v_mfma_f32_16x16x32_bf16 v[114:117], v[170:173], v[212:215], v[114:117]
	v_mfma_f32_16x16x32_bf16 v[118:121], v[204:207], v[212:215], v[118:121]
	v_mfma_f32_16x16x32_bf16 v[98:101], v[170:173], v[220:223], v[98:101]
	v_mfma_f32_16x16x32_bf16 v[102:105], v[204:207], v[220:223], v[102:105]
	v_mfma_f32_16x16x32_bf16 v[82:85], v[170:173], v[228:231], v[82:85]
	v_mfma_f32_16x16x32_bf16 v[86:89], v[204:207], v[228:231], v[86:89]
	v_mfma_f32_16x16x32_bf16 v[66:69], v[170:173], v[236:239], v[66:69]
	v_mfma_f32_16x16x32_bf16 v[70:73], v[204:207], v[236:239], v[70:73]
	v_mfma_f32_16x16x32_bf16 v[114:117], v[200:203], v[216:219], v[114:117]
	v_mfma_f32_16x16x32_bf16 v[118:121], v[208:211], v[216:219], v[118:121]
	v_mfma_f32_16x16x32_bf16 v[98:101], v[200:203], v[224:227], v[98:101]
	v_mfma_f32_16x16x32_bf16 v[102:105], v[208:211], v[224:227], v[102:105]
	v_mfma_f32_16x16x32_bf16 v[82:85], v[200:203], v[232:235], v[82:85]
	v_mfma_f32_16x16x32_bf16 v[86:89], v[208:211], v[232:235], v[86:89]
	s_setprio 2
	s_barrier
	v_mfma_f32_16x16x32_bf16 v[66:69], v[200:203], v[240:243], v[66:69]
	v_mfma_f32_16x16x32_bf16 v[70:73], v[208:211], v[240:243], v[70:73]
	s_setprio 0
	s_add_u32 s4, s64, 0x8000
	s_addc_u32 s5, s65, 0
	s_add_i32 s47, s36, s61
	s_mov_b32 m0, s47
	ds_read_b128 v[212:215], v194 offset:49152
	ds_read_b128 v[216:219], v194 offset:50176
	ds_read_b128 v[220:223], v194 offset:51200
	ds_read_b128 v[224:227], v194 offset:52224
	ds_read_b128 v[228:231], v194 offset:53248
	ds_read_b128 v[232:235], v194 offset:54272
	ds_read_b128 v[236:239], v194 offset:55296
	ds_read_b128 v[240:243], v194 offset:56320
	global_load_lds_dwordx4 v152, s[4:5] sc1
	s_add_i32 m0, s47, 0x2000
	s_nop 0
	global_load_lds_dwordx4 v154, s[4:5] sc1
	s_add_u32 s4, s64, 0xc000
	s_addc_u32 s5, s65, 0
	s_add_i32 s47, s37, s61
	s_mov_b32 m0, s47
	s_nop 0
	global_load_lds_dwordx4 v152, s[4:5] sc1
	s_add_i32 m0, s47, 0x2000
	s_nop 0
	global_load_lds_dwordx4 v154, s[4:5] sc1
	s_mov_b32 m0, s91
	s_nop 0
	global_load_lds_dwordx4 v150, s[56:57] sc1
	s_mov_b32 m0, s92
	s_nop 0
	global_load_lds_dwordx4 v148, s[56:57] sc1
	s_waitcnt vmcnt(8)
	s_waitcnt lgkmcnt(0)
	s_setprio 1
	s_barrier
	v_mfma_f32_16x16x32_bf16 v[58:61], v[130:133], v[212:215], v[58:61]
	v_mfma_f32_16x16x32_bf16 v[62:65], v[140:143], v[212:215], v[62:65]
	v_mfma_f32_16x16x32_bf16 v[42:45], v[130:133], v[220:223], v[42:45]
	v_mfma_f32_16x16x32_bf16 v[46:49], v[140:143], v[220:223], v[46:49]
	v_mfma_f32_16x16x32_bf16 v[26:29], v[130:133], v[228:231], v[26:29]
	v_mfma_f32_16x16x32_bf16 v[30:33], v[140:143], v[228:231], v[30:33]
	v_mfma_f32_16x16x32_bf16 v[10:13], v[130:133], v[236:239], v[10:13]
	v_mfma_f32_16x16x32_bf16 v[14:17], v[140:143], v[236:239], v[14:17]
	v_mfma_f32_16x16x32_bf16 v[58:61], v[136:139], v[216:219], v[58:61]
	v_mfma_f32_16x16x32_bf16 v[62:65], v[144:147], v[216:219], v[62:65]
	v_mfma_f32_16x16x32_bf16 v[42:45], v[136:139], v[224:227], v[42:45]
	v_mfma_f32_16x16x32_bf16 v[46:49], v[144:147], v[224:227], v[46:49]
	v_mfma_f32_16x16x32_bf16 v[26:29], v[136:139], v[232:235], v[26:29]
	v_mfma_f32_16x16x32_bf16 v[30:33], v[144:147], v[232:235], v[30:33]
	v_mfma_f32_16x16x32_bf16 v[10:13], v[136:139], v[240:243], v[10:13]
	v_mfma_f32_16x16x32_bf16 v[14:17], v[144:147], v[240:243], v[14:17]
	v_mfma_f32_16x16x32_bf16 v[50:53], v[170:173], v[212:215], v[50:53]
	v_mfma_f32_16x16x32_bf16 v[54:57], v[204:207], v[212:215], v[54:57]
	v_mfma_f32_16x16x32_bf16 v[34:37], v[170:173], v[220:223], v[34:37]
	v_mfma_f32_16x16x32_bf16 v[38:41], v[204:207], v[220:223], v[38:41]
	v_mfma_f32_16x16x32_bf16 v[18:21], v[170:173], v[228:231], v[18:21]
	v_mfma_f32_16x16x32_bf16 v[22:25], v[204:207], v[228:231], v[22:25]
	v_mfma_f32_16x16x32_bf16 v[2:5], v[170:173], v[236:239], v[2:5]
	v_mfma_f32_16x16x32_bf16 v[6:9], v[204:207], v[236:239], v[6:9]
	v_mfma_f32_16x16x32_bf16 v[50:53], v[200:203], v[216:219], v[50:53]
	v_mfma_f32_16x16x32_bf16 v[54:57], v[208:211], v[216:219], v[54:57]
	v_mfma_f32_16x16x32_bf16 v[34:37], v[200:203], v[224:227], v[34:37]
	v_mfma_f32_16x16x32_bf16 v[38:41], v[208:211], v[224:227], v[38:41]
	v_mfma_f32_16x16x32_bf16 v[18:21], v[200:203], v[232:235], v[18:21]
	v_mfma_f32_16x16x32_bf16 v[22:25], v[208:211], v[232:235], v[22:25]
	s_setprio 2
	s_barrier
	v_mfma_f32_16x16x32_bf16 v[2:5], v[200:203], v[240:243], v[2:5]
	v_mfma_f32_16x16x32_bf16 v[6:9], v[208:211], v[240:243], v[6:9]
	s_setprio 0
	s_add_i32 s46, s46, 2
	s_add_u32 s44, s44, 0x10000
	s_addc_u32 s45, s45, 0
	s_cmp_gt_u32 s46, 13
	s_mov_b64 s[4:5], s[8:9]
	s_cbranch_scc0 .LBB0_460
	s_and_b64 vcc, exec, s[70:71]
	s_cbranch_vccz .LBB0_463
	s_barrier

.LBB0_623:
	v_add_u32_e32 v160, s47, v142
	ds_read_b128 v[152:155], v160
	ds_read_b128 v[156:159], v160 offset:1024
	ds_read_b128 v[162:165], v160 offset:2048
	ds_read_b128 v[166:169], v160 offset:3072
	v_add_u32_e32 v160, s48, v142
	ds_read_b128 v[170:173], v160
	ds_read_b128 v[174:177], v160 offset:1024
	ds_read_b128 v[178:181], v160 offset:2048
	ds_read_b128 v[182:185], v160 offset:3072
	s_add_u32 s78, s70, 0x10000
	s_addc_u32 s79, s71, 0
	s_cmp_eq_u32 s94, 12
	s_cselect_b32 s92, s57, s78
	s_cselect_b32 s93, s55, s79
	s_cselect_b32 s90, s61, s69
	s_cselect_b32 s91, s11, s77
	s_add_u32 s82, s92, 0x8000
	s_addc_u32 s83, s93, 0
	s_add_i32 m0, s39, 0xc000
	ds_read_b128 v[192:195], v150
	ds_read_b128 v[200:203], v150 offset:1024
	ds_read_b128 v[204:207], v150 offset:2048
	ds_read_b128 v[208:211], v150 offset:3072
	ds_read_b128 v[212:215], v150 offset:4096
	ds_read_b128 v[216:219], v150 offset:5120
	ds_read_b128 v[220:223], v150 offset:6144
	ds_read_b128 v[224:227], v150 offset:7168
	global_load_lds_dwordx4 v138, s[70:71] sc1
	s_add_i32 m0, s39, 0xe000
	s_nop 0
	global_load_lds_dwordx4 v140, s[70:71] sc1
	s_waitcnt vmcnt(8)
	s_waitcnt lgkmcnt(0)
	s_setprio 1
	s_barrier
	v_mfma_f32_16x16x32_bf16 v[98:101], v[152:155], v[192:195], v[98:101]
	v_mfma_f32_16x16x32_bf16 v[102:105], v[162:165], v[192:195], v[102:105]
	v_mfma_f32_16x16x32_bf16 v[62:65], v[152:155], v[204:207], v[62:65]
	v_mfma_f32_16x16x32_bf16 v[78:81], v[162:165], v[204:207], v[78:81]
	v_mfma_f32_16x16x32_bf16 v[34:37], v[152:155], v[212:215], v[34:37]
	v_mfma_f32_16x16x32_bf16 v[46:49], v[162:165], v[212:215], v[46:49]
	v_mfma_f32_16x16x32_bf16 v[14:17], v[152:155], v[220:223], v[14:17]
	v_mfma_f32_16x16x32_bf16 v[22:25], v[162:165], v[220:223], v[22:25]
	v_mfma_f32_16x16x32_bf16 v[98:101], v[156:159], v[200:203], v[98:101]
	v_mfma_f32_16x16x32_bf16 v[102:105], v[166:169], v[200:203], v[102:105]
	v_mfma_f32_16x16x32_bf16 v[62:65], v[156:159], v[208:211], v[62:65]
	v_mfma_f32_16x16x32_bf16 v[78:81], v[166:169], v[208:211], v[78:81]
	v_mfma_f32_16x16x32_bf16 v[34:37], v[156:159], v[216:219], v[34:37]
	v_mfma_f32_16x16x32_bf16 v[46:49], v[166:169], v[216:219], v[46:49]
	v_mfma_f32_16x16x32_bf16 v[14:17], v[156:159], v[224:227], v[14:17]
	v_mfma_f32_16x16x32_bf16 v[22:25], v[166:169], v[224:227], v[22:25]
	v_mfma_f32_16x16x32_bf16 v[122:125], v[170:173], v[192:195], v[122:125]
	v_mfma_f32_16x16x32_bf16 v[126:129], v[178:181], v[192:195], v[126:129]
	v_mfma_f32_16x16x32_bf16 v[110:113], v[170:173], v[204:207], v[110:113]
	v_mfma_f32_16x16x32_bf16 v[118:121], v[178:181], v[204:207], v[118:121]
	v_mfma_f32_16x16x32_bf16 v[86:89], v[170:173], v[212:215], v[86:89]
	v_mfma_f32_16x16x32_bf16 v[94:97], v[178:181], v[212:215], v[94:97]
	v_mfma_f32_16x16x32_bf16 v[54:57], v[170:173], v[220:223], v[54:57]
	v_mfma_f32_16x16x32_bf16 v[70:73], v[178:181], v[220:223], v[70:73]
	v_mfma_f32_16x16x32_bf16 v[122:125], v[174:177], v[200:203], v[122:125]
	v_mfma_f32_16x16x32_bf16 v[126:129], v[182:185], v[200:203], v[126:129]
	v_mfma_f32_16x16x32_bf16 v[110:113], v[174:177], v[208:211], v[110:113]
	v_mfma_f32_16x16x32_bf16 v[118:121], v[182:185], v[208:211], v[118:121]
	v_mfma_f32_16x16x32_bf16 v[86:89], v[174:177], v[216:219], v[86:89]
	v_mfma_f32_16x16x32_bf16 v[94:97], v[182:185], v[216:219], v[94:97]
	s_setprio 2
	s_barrier
	v_mfma_f32_16x16x32_bf16 v[54:57], v[174:177], v[224:227], v[54:57]
	v_mfma_f32_16x16x32_bf16 v[70:73], v[182:185], v[224:227], v[70:73]
	s_setprio 0
	s_add_i32 s70, s47, s35
	s_mov_b32 m0, s70
	ds_read_b128 v[192:195], v150 offset:16384
	ds_read_b128 v[200:203], v150 offset:17408
	ds_read_b128 v[204:207], v150 offset:18432
	ds_read_b128 v[208:211], v150 offset:19456
	ds_read_b128 v[212:215], v150 offset:20480
	ds_read_b128 v[216:219], v150 offset:21504
	ds_read_b128 v[220:223], v150 offset:22528
	ds_read_b128 v[224:227], v150 offset:23552
	global_load_lds_dwordx4 v132, s[90:91] sc1
	s_add_i32 m0, s70, 0x2000
	s_add_u32 s70, s90, 0x4000
	s_addc_u32 s71, s91, 0
	s_add_i32 s95, s48, s35
	global_load_lds_dwordx4 v136, s[90:91] sc1
	s_mov_b32 m0, s95
	s_nop 0
	global_load_lds_dwordx4 v132, s[70:71] sc1
	s_add_i32 m0, s95, 0x2000
	s_nop 0
	global_load_lds_dwordx4 v136, s[70:71] sc1
	s_mov_b32 m0, s39
	s_nop 0
	global_load_lds_dwordx4 v130, s[92:93] sc1
	s_mov_b32 m0, s40
	s_nop 0
	global_load_lds_dwordx4 v134, s[92:93] sc1
	s_waitcnt vmcnt(8)
	s_waitcnt lgkmcnt(0)
	s_setprio 1
	s_barrier
	v_mfma_f32_16x16x32_bf16 v[58:61], v[152:155], v[192:195], v[58:61]
	v_mfma_f32_16x16x32_bf16 v[74:77], v[162:165], v[192:195], v[74:77]
	v_mfma_f32_16x16x32_bf16 v[30:33], v[152:155], v[204:207], v[30:33]
	v_mfma_f32_16x16x32_bf16 v[42:45], v[162:165], v[204:207], v[42:45]
	v_mfma_f32_16x16x32_bf16 v[10:13], v[152:155], v[212:215], v[10:13]
	v_mfma_f32_16x16x32_bf16 v[18:21], v[162:165], v[212:215], v[18:21]
	v_mfma_f32_16x16x32_bf16 v[2:5], v[152:155], v[220:223], v[2:5]
	v_mfma_f32_16x16x32_bf16 v[6:9], v[162:165], v[220:223], v[6:9]
	v_mfma_f32_16x16x32_bf16 v[58:61], v[156:159], v[200:203], v[58:61]
	v_mfma_f32_16x16x32_bf16 v[74:77], v[166:169], v[200:203], v[74:77]
	v_mfma_f32_16x16x32_bf16 v[30:33], v[156:159], v[208:211], v[30:33]
	v_mfma_f32_16x16x32_bf16 v[42:45], v[166:169], v[208:211], v[42:45]
	v_mfma_f32_16x16x32_bf16 v[10:13], v[156:159], v[216:219], v[10:13]
	v_mfma_f32_16x16x32_bf16 v[18:21], v[166:169], v[216:219], v[18:21]
	v_mfma_f32_16x16x32_bf16 v[2:5], v[156:159], v[224:227], v[2:5]
	v_mfma_f32_16x16x32_bf16 v[6:9], v[166:169], v[224:227], v[6:9]
	v_mfma_f32_16x16x32_bf16 v[106:109], v[170:173], v[192:195], v[106:109]
	v_mfma_f32_16x16x32_bf16 v[114:117], v[178:181], v[192:195], v[114:117]
	v_mfma_f32_16x16x32_bf16 v[82:85], v[170:173], v[204:207], v[82:85]
	v_mfma_f32_16x16x32_bf16 v[90:93], v[178:181], v[204:207], v[90:93]
	v_mfma_f32_16x16x32_bf16 v[50:53], v[170:173], v[212:215], v[50:53]
	v_mfma_f32_16x16x32_bf16 v[66:69], v[178:181], v[212:215], v[66:69]
	v_mfma_f32_16x16x32_bf16 v[26:29], v[170:173], v[220:223], v[26:29]
	v_mfma_f32_16x16x32_bf16 v[38:41], v[178:181], v[220:223], v[38:41]
	v_mfma_f32_16x16x32_bf16 v[106:109], v[174:177], v[200:203], v[106:109]
	v_mfma_f32_16x16x32_bf16 v[114:117], v[182:185], v[200:203], v[114:117]
	v_mfma_f32_16x16x32_bf16 v[82:85], v[174:177], v[208:211], v[82:85]
	v_mfma_f32_16x16x32_bf16 v[90:93], v[182:185], v[208:211], v[90:93]
	v_mfma_f32_16x16x32_bf16 v[50:53], v[174:177], v[216:219], v[50:53]
	v_mfma_f32_16x16x32_bf16 v[66:69], v[182:185], v[216:219], v[66:69]
	s_setprio 2
	s_barrier
	v_mfma_f32_16x16x32_bf16 v[26:29], v[174:177], v[224:227], v[26:29]
	v_mfma_f32_16x16x32_bf16 v[38:41], v[182:185], v[224:227], v[38:41]
	s_setprio 0
	v_add_u32_e32 v160, s49, v142
	ds_read_b128 v[152:155], v160
	ds_read_b128 v[156:159], v160 offset:1024
	ds_read_b128 v[162:165], v160 offset:2048
	ds_read_b128 v[166:169], v160 offset:3072
	v_add_u32_e32 v160, s50, v142
	ds_read_b128 v[170:173], v160
	ds_read_b128 v[174:177], v160 offset:1024
	ds_read_b128 v[178:181], v160 offset:2048
	ds_read_b128 v[182:185], v160 offset:3072
	s_add_u32 s70, s92, 0x4000
	s_addc_u32 s71, s93, 0
	s_mov_b32 m0, s41
	ds_read_b128 v[192:195], v150 offset:32768
	ds_read_b128 v[200:203], v150 offset:33792
	ds_read_b128 v[204:207], v150 offset:34816
	ds_read_b128 v[208:211], v150 offset:35840
	ds_read_b128 v[212:215], v150 offset:36864
	ds_read_b128 v[216:219], v150 offset:37888
	ds_read_b128 v[220:223], v150 offset:38912
	ds_read_b128 v[224:227], v150 offset:39936
	global_load_lds_dwordx4 v130, s[70:71] sc1
	s_mov_b32 m0, s42
	s_nop 0
	global_load_lds_dwordx4 v134, s[70:71] sc1
	s_waitcnt vmcnt(8)
	s_waitcnt lgkmcnt(0)
	s_setprio 1
	s_barrier
	v_mfma_f32_16x16x32_bf16 v[98:101], v[152:155], v[192:195], v[98:101]
	v_mfma_f32_16x16x32_bf16 v[102:105], v[162:165], v[192:195], v[102:105]
	v_mfma_f32_16x16x32_bf16 v[62:65], v[152:155], v[204:207], v[62:65]
	v_mfma_f32_16x16x32_bf16 v[78:81], v[162:165], v[204:207], v[78:81]
	v_mfma_f32_16x16x32_bf16 v[34:37], v[152:155], v[212:215], v[34:37]
	v_mfma_f32_16x16x32_bf16 v[46:49], v[162:165], v[212:215], v[46:49]
	v_mfma_f32_16x16x32_bf16 v[14:17], v[152:155], v[220:223], v[14:17]
	v_mfma_f32_16x16x32_bf16 v[22:25], v[162:165], v[220:223], v[22:25]
	v_mfma_f32_16x16x32_bf16 v[98:101], v[156:159], v[200:203], v[98:101]
	v_mfma_f32_16x16x32_bf16 v[102:105], v[166:169], v[200:203], v[102:105]
	v_mfma_f32_16x16x32_bf16 v[62:65], v[156:159], v[208:211], v[62:65]
	v_mfma_f32_16x16x32_bf16 v[78:81], v[166:169], v[208:211], v[78:81]
	v_mfma_f32_16x16x32_bf16 v[34:37], v[156:159], v[216:219], v[34:37]
	v_mfma_f32_16x16x32_bf16 v[46:49], v[166:169], v[216:219], v[46:49]
	v_mfma_f32_16x16x32_bf16 v[14:17], v[156:159], v[224:227], v[14:17]
	v_mfma_f32_16x16x32_bf16 v[22:25], v[166:169], v[224:227], v[22:25]
	v_mfma_f32_16x16x32_bf16 v[122:125], v[170:173], v[192:195], v[122:125]
	v_mfma_f32_16x16x32_bf16 v[126:129], v[178:181], v[192:195], v[126:129]
	v_mfma_f32_16x16x32_bf16 v[110:113], v[170:173], v[204:207], v[110:113]
	v_mfma_f32_16x16x32_bf16 v[118:121], v[178:181], v[204:207], v[118:121]
	v_mfma_f32_16x16x32_bf16 v[86:89], v[170:173], v[212:215], v[86:89]
	v_mfma_f32_16x16x32_bf16 v[94:97], v[178:181], v[212:215], v[94:97]
	v_mfma_f32_16x16x32_bf16 v[54:57], v[170:173], v[220:223], v[54:57]
	v_mfma_f32_16x16x32_bf16 v[70:73], v[178:181], v[220:223], v[70:73]
	v_mfma_f32_16x16x32_bf16 v[122:125], v[174:177], v[200:203], v[122:125]
	v_mfma_f32_16x16x32_bf16 v[126:129], v[182:185], v[200:203], v[126:129]
	v_mfma_f32_16x16x32_bf16 v[110:113], v[174:177], v[208:211], v[110:113]
	v_mfma_f32_16x16x32_bf16 v[118:121], v[182:185], v[208:211], v[118:121]
	v_mfma_f32_16x16x32_bf16 v[86:89], v[174:177], v[216:219], v[86:89]
	v_mfma_f32_16x16x32_bf16 v[94:97], v[182:185], v[216:219], v[94:97]
	s_setprio 2
	s_barrier
	v_mfma_f32_16x16x32_bf16 v[54:57], v[174:177], v[224:227], v[54:57]
	v_mfma_f32_16x16x32_bf16 v[70:73], v[182:185], v[224:227], v[70:73]
	s_setprio 0
	s_add_u32 s70, s90, 0x8000
	s_addc_u32 s71, s91, 0
	s_add_i32 s92, s49, s35
	s_mov_b32 m0, s92
	ds_read_b128 v[192:195], v150 offset:49152
	ds_read_b128 v[200:203], v150 offset:50176
	ds_read_b128 v[204:207], v150 offset:51200
	ds_read_b128 v[208:211], v150 offset:52224
	ds_read_b128 v[212:215], v150 offset:53248
	ds_read_b128 v[216:219], v150 offset:54272
	ds_read_b128 v[220:223], v150 offset:55296
	ds_read_b128 v[224:227], v150 offset:56320
	global_load_lds_dwordx4 v132, s[70:71] sc1
	s_add_i32 m0, s92, 0x2000
	s_nop 0
	global_load_lds_dwordx4 v136, s[70:71] sc1
	s_add_u32 s70, s90, 0xc000
	s_addc_u32 s71, s91, 0
	s_add_i32 s90, s50, s35
	s_mov_b32 m0, s90
	s_nop 0
	global_load_lds_dwordx4 v132, s[70:71] sc1
	s_add_i32 m0, s90, 0x2000
	s_nop 0
	global_load_lds_dwordx4 v136, s[70:71] sc1
	s_mov_b32 m0, s44
	s_nop 0
	global_load_lds_dwordx4 v130, s[82:83] sc1
	s_mov_b32 m0, s45
	s_nop 0
	global_load_lds_dwordx4 v134, s[82:83] sc1
	s_waitcnt vmcnt(8)
	s_waitcnt lgkmcnt(0)
	s_setprio 1
	s_barrier
	v_mfma_f32_16x16x32_bf16 v[58:61], v[152:155], v[192:195], v[58:61]
	v_mfma_f32_16x16x32_bf16 v[74:77], v[162:165], v[192:195], v[74:77]
	v_mfma_f32_16x16x32_bf16 v[30:33], v[152:155], v[204:207], v[30:33]
	v_mfma_f32_16x16x32_bf16 v[42:45], v[162:165], v[204:207], v[42:45]
	v_mfma_f32_16x16x32_bf16 v[10:13], v[152:155], v[212:215], v[10:13]
	v_mfma_f32_16x16x32_bf16 v[18:21], v[162:165], v[212:215], v[18:21]
	v_mfma_f32_16x16x32_bf16 v[2:5], v[152:155], v[220:223], v[2:5]
	v_mfma_f32_16x16x32_bf16 v[6:9], v[162:165], v[220:223], v[6:9]
	v_mfma_f32_16x16x32_bf16 v[58:61], v[156:159], v[200:203], v[58:61]
	v_mfma_f32_16x16x32_bf16 v[74:77], v[166:169], v[200:203], v[74:77]
	v_mfma_f32_16x16x32_bf16 v[30:33], v[156:159], v[208:211], v[30:33]
	v_mfma_f32_16x16x32_bf16 v[42:45], v[166:169], v[208:211], v[42:45]
	v_mfma_f32_16x16x32_bf16 v[10:13], v[156:159], v[216:219], v[10:13]
	v_mfma_f32_16x16x32_bf16 v[18:21], v[166:169], v[216:219], v[18:21]
	v_mfma_f32_16x16x32_bf16 v[2:5], v[156:159], v[224:227], v[2:5]
	v_mfma_f32_16x16x32_bf16 v[6:9], v[166:169], v[224:227], v[6:9]
	v_mfma_f32_16x16x32_bf16 v[106:109], v[170:173], v[192:195], v[106:109]
	v_mfma_f32_16x16x32_bf16 v[114:117], v[178:181], v[192:195], v[114:117]
	v_mfma_f32_16x16x32_bf16 v[82:85], v[170:173], v[204:207], v[82:85]
	v_mfma_f32_16x16x32_bf16 v[90:93], v[178:181], v[204:207], v[90:93]
	v_mfma_f32_16x16x32_bf16 v[50:53], v[170:173], v[212:215], v[50:53]
	v_mfma_f32_16x16x32_bf16 v[66:69], v[178:181], v[212:215], v[66:69]
	v_mfma_f32_16x16x32_bf16 v[26:29], v[170:173], v[220:223], v[26:29]
	v_mfma_f32_16x16x32_bf16 v[38:41], v[178:181], v[220:223], v[38:41]
	v_mfma_f32_16x16x32_bf16 v[106:109], v[174:177], v[200:203], v[106:109]
	v_mfma_f32_16x16x32_bf16 v[114:117], v[182:185], v[200:203], v[114:117]
	v_mfma_f32_16x16x32_bf16 v[82:85], v[174:177], v[208:211], v[82:85]
	v_mfma_f32_16x16x32_bf16 v[90:93], v[182:185], v[208:211], v[90:93]
	v_mfma_f32_16x16x32_bf16 v[50:53], v[174:177], v[216:219], v[50:53]
	v_mfma_f32_16x16x32_bf16 v[66:69], v[182:185], v[216:219], v[66:69]
	s_setprio 2
	s_barrier
	v_mfma_f32_16x16x32_bf16 v[26:29], v[174:177], v[224:227], v[26:29]
	v_mfma_f32_16x16x32_bf16 v[38:41], v[182:185], v[224:227], v[38:41]
	s_setprio 0
	s_add_i32 s94, s94, 2
	s_add_u32 s69, s69, 0x10000
	s_addc_u32 s77, s77, 0
	s_cmp_gt_u32 s94, 13
	s_mov_b64 s[70:71], s[78:79]
	s_cbranch_scc0 .LBB0_623
	s_and_b64 vcc, exec, s[8:9]
	s_cbranch_vccz .LBB0_626
	s_barrier

.LBB0_884:
	s_add_u32 s19, s38, s64
	s_addc_u32 s41, s39, s65
	v_add_u32_e32 v168, s49, v151
	v_add_u32_e32 v184, s51, v151
	s_add_u32 s19, s19, 0x10000
	ds_read_b128 v[156:159], v168
	ds_read_b128 v[160:163], v168 offset:1024
	ds_read_b128 v[164:167], v168 offset:2048
	ds_read_b128 v[168:171], v168 offset:3072
	ds_read_b128 v[172:175], v184
	ds_read_b128 v[176:179], v184 offset:1024
	ds_read_b128 v[180:183], v184 offset:2048
	ds_read_b128 v[184:187], v184 offset:3072
	s_addc_u32 s41, s41, 0
	s_add_u32 s66, s69, s64
	s_addc_u32 s67, s80, s65
	s_cmp_eq_u32 s64, 0x70000
	s_cselect_b32 s78, s81, s19
	s_cselect_b32 s79, s57, s41
	s_cselect_b32 s70, s86, s66
	s_cselect_b32 s71, s85, s67
	s_add_u32 s66, s78, 0x8000
	s_addc_u32 s67, s79, 0
	s_add_i32 s19, s37, 0xc000
	v_lshl_add_u64 v[196:197], v[144:145], 0, s[64:65]
	s_mov_b32 m0, s19
	s_add_i32 s41, s37, 0xe000
	ds_read_b128 v[192:195], v154
	ds_read_b128 v[200:203], v154 offset:1024
	ds_read_b128 v[204:207], v154 offset:2048
	ds_read_b128 v[208:211], v154 offset:3072
	ds_read_b128 v[212:215], v154 offset:4096
	ds_read_b128 v[216:219], v154 offset:5120
	ds_read_b128 v[220:223], v154 offset:6144
	ds_read_b128 v[224:227], v154 offset:7168
	global_load_lds_dwordx4 v[196:197], off sc1
	v_lshl_add_u64 v[196:197], v[146:147], 0, s[64:65]
	s_mov_b32 m0, s41
	s_nop 0
	global_load_lds_dwordx4 v[196:197], off sc1
	s_waitcnt vmcnt(8)
	s_waitcnt lgkmcnt(0)
	s_setprio 1
	s_barrier
	v_mfma_f32_16x16x32_bf16 v[112:115], v[156:159], v[192:195], v[112:115]
	v_mfma_f32_16x16x32_bf16 v[116:119], v[164:167], v[192:195], v[116:119]
	v_mfma_f32_16x16x32_bf16 v[96:99], v[156:159], v[204:207], v[96:99]
	v_mfma_f32_16x16x32_bf16 v[100:103], v[164:167], v[204:207], v[100:103]
	v_mfma_f32_16x16x32_bf16 v[80:83], v[156:159], v[212:215], v[80:83]
	v_mfma_f32_16x16x32_bf16 v[84:87], v[164:167], v[212:215], v[84:87]
	v_mfma_f32_16x16x32_bf16 v[64:67], v[156:159], v[220:223], v[64:67]
	v_mfma_f32_16x16x32_bf16 v[68:71], v[164:167], v[220:223], v[68:71]
	v_mfma_f32_16x16x32_bf16 v[112:115], v[160:163], v[200:203], v[112:115]
	v_mfma_f32_16x16x32_bf16 v[116:119], v[168:171], v[200:203], v[116:119]
	v_mfma_f32_16x16x32_bf16 v[96:99], v[160:163], v[208:211], v[96:99]
	v_mfma_f32_16x16x32_bf16 v[100:103], v[168:171], v[208:211], v[100:103]
	v_mfma_f32_16x16x32_bf16 v[80:83], v[160:163], v[216:219], v[80:83]
	v_mfma_f32_16x16x32_bf16 v[84:87], v[168:171], v[216:219], v[84:87]
	v_mfma_f32_16x16x32_bf16 v[64:67], v[160:163], v[224:227], v[64:67]
	v_mfma_f32_16x16x32_bf16 v[68:71], v[168:171], v[224:227], v[68:71]
	v_mfma_f32_16x16x32_bf16 v[120:123], v[172:175], v[192:195], v[120:123]
	v_mfma_f32_16x16x32_bf16 v[124:127], v[180:183], v[192:195], v[124:127]
	v_mfma_f32_16x16x32_bf16 v[104:107], v[172:175], v[204:207], v[104:107]
	v_mfma_f32_16x16x32_bf16 v[108:111], v[180:183], v[204:207], v[108:111]
	v_mfma_f32_16x16x32_bf16 v[88:91], v[172:175], v[212:215], v[88:91]
	v_mfma_f32_16x16x32_bf16 v[92:95], v[180:183], v[212:215], v[92:95]
	v_mfma_f32_16x16x32_bf16 v[72:75], v[172:175], v[220:223], v[72:75]
	v_mfma_f32_16x16x32_bf16 v[76:79], v[180:183], v[220:223], v[76:79]
	v_mfma_f32_16x16x32_bf16 v[120:123], v[176:179], v[200:203], v[120:123]
	v_mfma_f32_16x16x32_bf16 v[124:127], v[184:187], v[200:203], v[124:127]
	v_mfma_f32_16x16x32_bf16 v[104:107], v[176:179], v[208:211], v[104:107]
	v_mfma_f32_16x16x32_bf16 v[108:111], v[184:187], v[208:211], v[108:111]
	v_mfma_f32_16x16x32_bf16 v[88:91], v[176:179], v[216:219], v[88:91]
	v_mfma_f32_16x16x32_bf16 v[92:95], v[184:187], v[216:219], v[92:95]
	s_setprio 2
	s_barrier
	v_mfma_f32_16x16x32_bf16 v[72:75], v[176:179], v[224:227], v[72:75]
	v_mfma_f32_16x16x32_bf16 v[76:79], v[184:187], v[224:227], v[76:79]
	s_setprio 0
	s_add_i32 s88, s49, s35
	s_mov_b32 m0, s88
	ds_read_b128 v[192:195], v154 offset:16384
	ds_read_b128 v[200:203], v154 offset:17408
	ds_read_b128 v[204:207], v154 offset:18432
	ds_read_b128 v[208:211], v154 offset:19456
	ds_read_b128 v[212:215], v154 offset:20480
	ds_read_b128 v[216:219], v154 offset:21504
	ds_read_b128 v[220:223], v154 offset:22528
	ds_read_b128 v[224:227], v154 offset:23552
	global_load_lds_dwordx4 v130, s[70:71] sc1
	s_add_i32 m0, s88, 0x2000
	s_add_u32 s88, s70, 0x4000
	s_addc_u32 s89, s71, 0
	s_add_i32 s90, s51, s35
	global_load_lds_dwordx4 v134, s[70:71] sc1
	s_mov_b32 m0, s90
	s_nop 0
	global_load_lds_dwordx4 v130, s[88:89] sc1
	s_add_i32 m0, s90, 0x2000
	s_nop 0
	global_load_lds_dwordx4 v134, s[88:89] sc1
	s_mov_b32 m0, s37
	s_nop 0
	global_load_lds_dwordx4 v128, s[78:79] sc1
	s_mov_b32 m0, s43
	s_nop 0
	global_load_lds_dwordx4 v132, s[78:79] sc1
	s_waitcnt vmcnt(8)
	s_waitcnt lgkmcnt(0)
	s_setprio 1
	s_barrier
	v_mfma_f32_16x16x32_bf16 v[48:51], v[156:159], v[192:195], v[48:51]
	v_mfma_f32_16x16x32_bf16 v[52:55], v[164:167], v[192:195], v[52:55]
	v_mfma_f32_16x16x32_bf16 v[32:35], v[156:159], v[204:207], v[32:35]
	v_mfma_f32_16x16x32_bf16 v[36:39], v[164:167], v[204:207], v[36:39]
	v_mfma_f32_16x16x32_bf16 v[16:19], v[156:159], v[212:215], v[16:19]
	v_mfma_f32_16x16x32_bf16 v[20:23], v[164:167], v[212:215], v[20:23]
	v_mfma_f32_16x16x32_bf16 v[0:3], v[156:159], v[220:223], v[0:3]
	v_mfma_f32_16x16x32_bf16 v[4:7], v[164:167], v[220:223], v[4:7]
	v_mfma_f32_16x16x32_bf16 v[48:51], v[160:163], v[200:203], v[48:51]
	v_mfma_f32_16x16x32_bf16 v[52:55], v[168:171], v[200:203], v[52:55]
	v_mfma_f32_16x16x32_bf16 v[32:35], v[160:163], v[208:211], v[32:35]
	v_mfma_f32_16x16x32_bf16 v[36:39], v[168:171], v[208:211], v[36:39]
	v_mfma_f32_16x16x32_bf16 v[16:19], v[160:163], v[216:219], v[16:19]
	v_mfma_f32_16x16x32_bf16 v[20:23], v[168:171], v[216:219], v[20:23]
	v_mfma_f32_16x16x32_bf16 v[0:3], v[160:163], v[224:227], v[0:3]
	v_mfma_f32_16x16x32_bf16 v[4:7], v[168:171], v[224:227], v[4:7]
	v_mfma_f32_16x16x32_bf16 v[56:59], v[172:175], v[192:195], v[56:59]
	v_mfma_f32_16x16x32_bf16 v[60:63], v[180:183], v[192:195], v[60:63]
	v_mfma_f32_16x16x32_bf16 v[40:43], v[172:175], v[204:207], v[40:43]
	v_mfma_f32_16x16x32_bf16 v[44:47], v[180:183], v[204:207], v[44:47]
	v_mfma_f32_16x16x32_bf16 v[24:27], v[172:175], v[212:215], v[24:27]
	v_mfma_f32_16x16x32_bf16 v[28:31], v[180:183], v[212:215], v[28:31]
	v_mfma_f32_16x16x32_bf16 v[8:11], v[172:175], v[220:223], v[8:11]
	v_mfma_f32_16x16x32_bf16 v[12:15], v[180:183], v[220:223], v[12:15]
	v_mfma_f32_16x16x32_bf16 v[56:59], v[176:179], v[200:203], v[56:59]
	v_mfma_f32_16x16x32_bf16 v[60:63], v[184:187], v[200:203], v[60:63]
	v_mfma_f32_16x16x32_bf16 v[40:43], v[176:179], v[208:211], v[40:43]
	v_mfma_f32_16x16x32_bf16 v[44:47], v[184:187], v[208:211], v[44:47]
	v_mfma_f32_16x16x32_bf16 v[24:27], v[176:179], v[216:219], v[24:27]
	v_mfma_f32_16x16x32_bf16 v[28:31], v[184:187], v[216:219], v[28:31]
	s_setprio 2
	s_barrier
	v_mfma_f32_16x16x32_bf16 v[8:11], v[176:179], v[224:227], v[8:11]
	v_mfma_f32_16x16x32_bf16 v[12:15], v[184:187], v[224:227], v[12:15]
	s_setprio 0
	v_add_u32_e32 v168, s54, v151
	v_add_u32_e32 v184, s55, v151
	ds_read_b128 v[156:159], v168
	ds_read_b128 v[160:163], v168 offset:1024
	ds_read_b128 v[164:167], v168 offset:2048
	ds_read_b128 v[168:171], v168 offset:3072
	ds_read_b128 v[172:175], v184
	ds_read_b128 v[176:179], v184 offset:1024
	ds_read_b128 v[180:183], v184 offset:2048
	ds_read_b128 v[184:187], v184 offset:3072
	s_add_u32 s78, s78, 0x4000
	s_addc_u32 s79, s79, 0
	s_mov_b32 m0, s44
	ds_read_b128 v[192:195], v154 offset:32768
	ds_read_b128 v[200:203], v154 offset:33792
	ds_read_b128 v[204:207], v154 offset:34816
	ds_read_b128 v[208:211], v154 offset:35840
	ds_read_b128 v[212:215], v154 offset:36864
	ds_read_b128 v[216:219], v154 offset:37888
	ds_read_b128 v[220:223], v154 offset:38912
	ds_read_b128 v[224:227], v154 offset:39936
	global_load_lds_dwordx4 v128, s[78:79] sc1
	s_mov_b32 m0, s45
	s_nop 0
	global_load_lds_dwordx4 v132, s[78:79] sc1
	s_waitcnt vmcnt(8)
	s_waitcnt lgkmcnt(0)
	s_setprio 1
	s_barrier
	v_mfma_f32_16x16x32_bf16 v[112:115], v[156:159], v[192:195], v[112:115]
	v_mfma_f32_16x16x32_bf16 v[116:119], v[164:167], v[192:195], v[116:119]
	v_mfma_f32_16x16x32_bf16 v[96:99], v[156:159], v[204:207], v[96:99]
	v_mfma_f32_16x16x32_bf16 v[100:103], v[164:167], v[204:207], v[100:103]
	v_mfma_f32_16x16x32_bf16 v[80:83], v[156:159], v[212:215], v[80:83]
	v_mfma_f32_16x16x32_bf16 v[84:87], v[164:167], v[212:215], v[84:87]
	v_mfma_f32_16x16x32_bf16 v[64:67], v[156:159], v[220:223], v[64:67]
	v_mfma_f32_16x16x32_bf16 v[68:71], v[164:167], v[220:223], v[68:71]
	v_mfma_f32_16x16x32_bf16 v[112:115], v[160:163], v[200:203], v[112:115]
	v_mfma_f32_16x16x32_bf16 v[116:119], v[168:171], v[200:203], v[116:119]
	v_mfma_f32_16x16x32_bf16 v[96:99], v[160:163], v[208:211], v[96:99]
	v_mfma_f32_16x16x32_bf16 v[100:103], v[168:171], v[208:211], v[100:103]
	v_mfma_f32_16x16x32_bf16 v[80:83], v[160:163], v[216:219], v[80:83]
	v_mfma_f32_16x16x32_bf16 v[84:87], v[168:171], v[216:219], v[84:87]
	v_mfma_f32_16x16x32_bf16 v[64:67], v[160:163], v[224:227], v[64:67]
	v_mfma_f32_16x16x32_bf16 v[68:71], v[168:171], v[224:227], v[68:71]
	v_mfma_f32_16x16x32_bf16 v[120:123], v[172:175], v[192:195], v[120:123]
	v_mfma_f32_16x16x32_bf16 v[124:127], v[180:183], v[192:195], v[124:127]
	v_mfma_f32_16x16x32_bf16 v[104:107], v[172:175], v[204:207], v[104:107]
	v_mfma_f32_16x16x32_bf16 v[108:111], v[180:183], v[204:207], v[108:111]
	v_mfma_f32_16x16x32_bf16 v[88:91], v[172:175], v[212:215], v[88:91]
	v_mfma_f32_16x16x32_bf16 v[92:95], v[180:183], v[212:215], v[92:95]
	v_mfma_f32_16x16x32_bf16 v[72:75], v[172:175], v[220:223], v[72:75]
	v_mfma_f32_16x16x32_bf16 v[76:79], v[180:183], v[220:223], v[76:79]
	v_mfma_f32_16x16x32_bf16 v[120:123], v[176:179], v[200:203], v[120:123]
	v_mfma_f32_16x16x32_bf16 v[124:127], v[184:187], v[200:203], v[124:127]
	v_mfma_f32_16x16x32_bf16 v[104:107], v[176:179], v[208:211], v[104:107]
	v_mfma_f32_16x16x32_bf16 v[108:111], v[184:187], v[208:211], v[108:111]
	v_mfma_f32_16x16x32_bf16 v[88:91], v[176:179], v[216:219], v[88:91]
	v_mfma_f32_16x16x32_bf16 v[92:95], v[184:187], v[216:219], v[92:95]
	s_setprio 2
	s_barrier
	v_mfma_f32_16x16x32_bf16 v[72:75], v[176:179], v[224:227], v[72:75]
	v_mfma_f32_16x16x32_bf16 v[76:79], v[184:187], v[224:227], v[76:79]
	s_setprio 0
	s_add_u32 s78, s70, 0x8000
	s_addc_u32 s79, s71, 0
	s_add_i32 s88, s54, s35
	s_mov_b32 m0, s88
	ds_read_b128 v[192:195], v154 offset:49152
	ds_read_b128 v[200:203], v154 offset:50176
	ds_read_b128 v[204:207], v154 offset:51200
	ds_read_b128 v[208:211], v154 offset:52224
	ds_read_b128 v[212:215], v154 offset:53248
	ds_read_b128 v[216:219], v154 offset:54272
	ds_read_b128 v[220:223], v154 offset:55296
	ds_read_b128 v[224:227], v154 offset:56320
	global_load_lds_dwordx4 v130, s[78:79] sc1
	s_add_i32 m0, s88, 0x2000
	s_add_u32 s70, s70, 0xc000
	global_load_lds_dwordx4 v134, s[78:79] sc1
	s_addc_u32 s71, s71, 0
	s_add_i32 s78, s55, s35
	s_mov_b32 m0, s78
	s_nop 0
	global_load_lds_dwordx4 v130, s[70:71] sc1
	s_add_i32 m0, s78, 0x2000
	s_nop 0
	global_load_lds_dwordx4 v134, s[70:71] sc1
	s_mov_b32 m0, s47
	s_nop 0
	global_load_lds_dwordx4 v128, s[66:67] sc1
	s_mov_b32 m0, s48
	s_nop 0
	global_load_lds_dwordx4 v132, s[66:67] sc1
	s_waitcnt vmcnt(8)
	s_waitcnt lgkmcnt(0)
	s_setprio 1
	s_barrier
	v_mfma_f32_16x16x32_bf16 v[48:51], v[156:159], v[192:195], v[48:51]
	v_mfma_f32_16x16x32_bf16 v[52:55], v[164:167], v[192:195], v[52:55]
	v_mfma_f32_16x16x32_bf16 v[32:35], v[156:159], v[204:207], v[32:35]
	v_mfma_f32_16x16x32_bf16 v[36:39], v[164:167], v[204:207], v[36:39]
	v_mfma_f32_16x16x32_bf16 v[16:19], v[156:159], v[212:215], v[16:19]
	v_mfma_f32_16x16x32_bf16 v[20:23], v[164:167], v[212:215], v[20:23]
	v_mfma_f32_16x16x32_bf16 v[0:3], v[156:159], v[220:223], v[0:3]
	v_mfma_f32_16x16x32_bf16 v[4:7], v[164:167], v[220:223], v[4:7]
	v_mfma_f32_16x16x32_bf16 v[48:51], v[160:163], v[200:203], v[48:51]
	v_mfma_f32_16x16x32_bf16 v[52:55], v[168:171], v[200:203], v[52:55]
	v_mfma_f32_16x16x32_bf16 v[32:35], v[160:163], v[208:211], v[32:35]
	v_mfma_f32_16x16x32_bf16 v[36:39], v[168:171], v[208:211], v[36:39]
	v_mfma_f32_16x16x32_bf16 v[16:19], v[160:163], v[216:219], v[16:19]
	v_mfma_f32_16x16x32_bf16 v[20:23], v[168:171], v[216:219], v[20:23]
	v_mfma_f32_16x16x32_bf16 v[0:3], v[160:163], v[224:227], v[0:3]
	v_mfma_f32_16x16x32_bf16 v[4:7], v[168:171], v[224:227], v[4:7]
	v_mfma_f32_16x16x32_bf16 v[56:59], v[172:175], v[192:195], v[56:59]
	v_mfma_f32_16x16x32_bf16 v[60:63], v[180:183], v[192:195], v[60:63]
	v_mfma_f32_16x16x32_bf16 v[40:43], v[172:175], v[204:207], v[40:43]
	v_mfma_f32_16x16x32_bf16 v[44:47], v[180:183], v[204:207], v[44:47]
	v_mfma_f32_16x16x32_bf16 v[24:27], v[172:175], v[212:215], v[24:27]
	v_mfma_f32_16x16x32_bf16 v[28:31], v[180:183], v[212:215], v[28:31]
	v_mfma_f32_16x16x32_bf16 v[8:11], v[172:175], v[220:223], v[8:11]
	v_mfma_f32_16x16x32_bf16 v[12:15], v[180:183], v[220:223], v[12:15]
	v_mfma_f32_16x16x32_bf16 v[56:59], v[176:179], v[200:203], v[56:59]
	v_mfma_f32_16x16x32_bf16 v[60:63], v[184:187], v[200:203], v[60:63]
	v_mfma_f32_16x16x32_bf16 v[40:43], v[176:179], v[208:211], v[40:43]
	v_mfma_f32_16x16x32_bf16 v[44:47], v[184:187], v[208:211], v[44:47]
	v_mfma_f32_16x16x32_bf16 v[24:27], v[176:179], v[216:219], v[24:27]
	v_mfma_f32_16x16x32_bf16 v[28:31], v[184:187], v[216:219], v[28:31]
	s_setprio 2
	s_barrier
	v_mfma_f32_16x16x32_bf16 v[8:11], v[176:179], v[224:227], v[8:11]
	v_mfma_f32_16x16x32_bf16 v[12:15], v[184:187], v[224:227], v[12:15]
	s_setprio 0
	s_add_i32 s87, s87, 2
	s_add_u32 s64, s64, 0x10000
	s_addc_u32 s65, s65, 0
	s_cmp_gt_u32 s87, 13
	s_cbranch_scc0 .LBB0_884
	s_add_u32 s64, s69, 0xffff0000
	s_addc_u32 s65, s80, -1
	s_andn2_b64 vcc, exec, s[8:9]
	s_cbranch_vccz .LBB0_876
	s_mov_b64 s[30:31], s[64:65]
	s_andn2_b64 vcc, exec, s[6:7]
	s_cbranch_vccnz .LBB0_877

.LBB0_976:
	s_add_u32 s66, s18, s64
	v_add_u32_e32 v151, s48, v149
	s_addc_u32 s67, s19, s65
	ds_read_b128 v[152:155], v151
	ds_read_b128 v[156:159], v151 offset:1024
	ds_read_b128 v[160:163], v151 offset:2048
	ds_read_b128 v[164:167], v151 offset:3072
	v_add_u32_e32 v151, s49, v149
	s_add_u32 s66, s66, 0x10000
	ds_read_b128 v[168:171], v151
	ds_read_b128 v[172:175], v151 offset:1024
	ds_read_b128 v[176:179], v151 offset:2048
	ds_read_b128 v[180:183], v151 offset:3072
	s_addc_u32 s67, s67, 0
	s_add_u32 s70, s55, s64
	s_addc_u32 s71, s69, s65
	s_cmp_eq_u32 s64, 0x70000
	s_cselect_b32 s78, s80, s66
	s_cselect_b32 s79, s41, s67
	s_cselect_b32 s70, s81, s70
	s_cselect_b32 s71, s39, s71
	s_add_u32 s66, s78, 0x8000
	s_addc_u32 s67, s79, 0
	v_lshl_add_u64 v[196:197], v[144:145], 0, s[64:65]
	s_add_i32 m0, s11, 0xc000
	ds_read_b128 v[184:187], v150
	ds_read_b128 v[192:195], v150 offset:1024
	ds_read_b128 v[200:203], v150 offset:2048
	ds_read_b128 v[204:207], v150 offset:3072
	ds_read_b128 v[208:211], v150 offset:4096
	ds_read_b128 v[212:215], v150 offset:5120
	ds_read_b128 v[216:219], v150 offset:6144
	ds_read_b128 v[220:223], v150 offset:7168
	global_load_lds_dwordx4 v[196:197], off sc1
	v_lshl_add_u64 v[196:197], v[146:147], 0, s[64:65]
	s_add_i32 m0, s11, 0xe000
	s_nop 0
	global_load_lds_dwordx4 v[196:197], off sc1
	s_waitcnt vmcnt(8)
	s_waitcnt lgkmcnt(0)
	s_setprio 1
	s_barrier
	v_mfma_f32_16x16x32_bf16 v[104:107], v[152:155], v[184:187], v[104:107]
	v_mfma_f32_16x16x32_bf16 v[108:111], v[160:163], v[184:187], v[108:111]
	v_mfma_f32_16x16x32_bf16 v[84:87], v[152:155], v[200:203], v[84:87]
	v_mfma_f32_16x16x32_bf16 v[92:95], v[160:163], v[200:203], v[92:95]
	v_mfma_f32_16x16x32_bf16 v[72:75], v[152:155], v[208:211], v[72:75]
	v_mfma_f32_16x16x32_bf16 v[76:79], v[160:163], v[208:211], v[76:79]
	v_mfma_f32_16x16x32_bf16 v[64:67], v[152:155], v[216:219], v[64:67]
	v_mfma_f32_16x16x32_bf16 v[68:71], v[160:163], v[216:219], v[68:71]
	v_mfma_f32_16x16x32_bf16 v[104:107], v[156:159], v[192:195], v[104:107]
	v_mfma_f32_16x16x32_bf16 v[108:111], v[164:167], v[192:195], v[108:111]
	v_mfma_f32_16x16x32_bf16 v[84:87], v[156:159], v[204:207], v[84:87]
	v_mfma_f32_16x16x32_bf16 v[92:95], v[164:167], v[204:207], v[92:95]
	v_mfma_f32_16x16x32_bf16 v[72:75], v[156:159], v[212:215], v[72:75]
	v_mfma_f32_16x16x32_bf16 v[76:79], v[164:167], v[212:215], v[76:79]
	v_mfma_f32_16x16x32_bf16 v[64:67], v[156:159], v[220:223], v[64:67]
	v_mfma_f32_16x16x32_bf16 v[68:71], v[164:167], v[220:223], v[68:71]
	v_mfma_f32_16x16x32_bf16 v[120:123], v[168:171], v[184:187], v[120:123]
	v_mfma_f32_16x16x32_bf16 v[124:127], v[176:179], v[184:187], v[124:127]
	v_mfma_f32_16x16x32_bf16 v[112:115], v[168:171], v[200:203], v[112:115]
	v_mfma_f32_16x16x32_bf16 v[116:119], v[176:179], v[200:203], v[116:119]
	v_mfma_f32_16x16x32_bf16 v[96:99], v[168:171], v[208:211], v[96:99]
	v_mfma_f32_16x16x32_bf16 v[100:103], v[176:179], v[208:211], v[100:103]
	v_mfma_f32_16x16x32_bf16 v[80:83], v[168:171], v[216:219], v[80:83]
	v_mfma_f32_16x16x32_bf16 v[88:91], v[176:179], v[216:219], v[88:91]
	v_mfma_f32_16x16x32_bf16 v[120:123], v[172:175], v[192:195], v[120:123]
	v_mfma_f32_16x16x32_bf16 v[124:127], v[180:183], v[192:195], v[124:127]
	v_mfma_f32_16x16x32_bf16 v[112:115], v[172:175], v[204:207], v[112:115]
	v_mfma_f32_16x16x32_bf16 v[116:119], v[180:183], v[204:207], v[116:119]
	v_mfma_f32_16x16x32_bf16 v[96:99], v[172:175], v[212:215], v[96:99]
	v_mfma_f32_16x16x32_bf16 v[100:103], v[180:183], v[212:215], v[100:103]
	s_setprio 2
	s_barrier
	v_mfma_f32_16x16x32_bf16 v[80:83], v[172:175], v[220:223], v[80:83]
	v_mfma_f32_16x16x32_bf16 v[88:91], v[180:183], v[220:223], v[88:91]
	s_setprio 0
	s_add_i32 s86, s48, s37
	s_mov_b32 m0, s86
	ds_read_b128 v[184:187], v150 offset:16384
	ds_read_b128 v[192:195], v150 offset:17408
	ds_read_b128 v[200:203], v150 offset:18432
	ds_read_b128 v[204:207], v150 offset:19456
	ds_read_b128 v[208:211], v150 offset:20480
	ds_read_b128 v[212:215], v150 offset:21504
	ds_read_b128 v[216:219], v150 offset:22528
	ds_read_b128 v[220:223], v150 offset:23552
	global_load_lds_dwordx4 v132, s[70:71] sc1
	s_add_i32 m0, s86, 0x2000
	s_add_u32 s86, s70, 0x4000
	s_addc_u32 s87, s71, 0
	s_add_i32 s88, s49, s37
	global_load_lds_dwordx4 v134, s[70:71] sc1
	s_mov_b32 m0, s88
	s_nop 0
	global_load_lds_dwordx4 v132, s[86:87] sc1
	s_add_i32 m0, s88, 0x2000
	s_nop 0
	global_load_lds_dwordx4 v134, s[86:87] sc1
	s_mov_b32 m0, s11
	s_nop 0
	global_load_lds_dwordx4 v128, s[78:79] sc1
	s_mov_b32 m0, s42
	s_nop 0
	global_load_lds_dwordx4 v130, s[78:79] sc1
	s_waitcnt vmcnt(8)
	s_waitcnt lgkmcnt(0)
	s_setprio 1
	s_barrier
	v_mfma_f32_16x16x32_bf16 v[36:39], v[152:155], v[184:187], v[36:39]
	v_mfma_f32_16x16x32_bf16 v[44:47], v[160:163], v[184:187], v[44:47]
	v_mfma_f32_16x16x32_bf16 v[20:23], v[152:155], v[200:203], v[20:23]
	v_mfma_f32_16x16x32_bf16 v[28:31], v[160:163], v[200:203], v[28:31]
	v_mfma_f32_16x16x32_bf16 v[8:11], v[152:155], v[208:211], v[8:11]
	v_mfma_f32_16x16x32_bf16 v[12:15], v[160:163], v[208:211], v[12:15]
	v_mfma_f32_16x16x32_bf16 v[0:3], v[152:155], v[216:219], v[0:3]
	v_mfma_f32_16x16x32_bf16 v[4:7], v[160:163], v[216:219], v[4:7]
	v_mfma_f32_16x16x32_bf16 v[36:39], v[156:159], v[192:195], v[36:39]
	v_mfma_f32_16x16x32_bf16 v[44:47], v[164:167], v[192:195], v[44:47]
	v_mfma_f32_16x16x32_bf16 v[20:23], v[156:159], v[204:207], v[20:23]
	v_mfma_f32_16x16x32_bf16 v[28:31], v[164:167], v[204:207], v[28:31]
	v_mfma_f32_16x16x32_bf16 v[8:11], v[156:159], v[212:215], v[8:11]
	v_mfma_f32_16x16x32_bf16 v[12:15], v[164:167], v[212:215], v[12:15]
	v_mfma_f32_16x16x32_bf16 v[0:3], v[156:159], v[220:223], v[0:3]
	v_mfma_f32_16x16x32_bf16 v[4:7], v[164:167], v[220:223], v[4:7]
	v_mfma_f32_16x16x32_bf16 v[56:59], v[168:171], v[184:187], v[56:59]
	v_mfma_f32_16x16x32_bf16 v[60:63], v[176:179], v[184:187], v[60:63]
	v_mfma_f32_16x16x32_bf16 v[48:51], v[168:171], v[200:203], v[48:51]
	v_mfma_f32_16x16x32_bf16 v[52:55], v[176:179], v[200:203], v[52:55]
	v_mfma_f32_16x16x32_bf16 v[32:35], v[168:171], v[208:211], v[32:35]
	v_mfma_f32_16x16x32_bf16 v[40:43], v[176:179], v[208:211], v[40:43]
	v_mfma_f32_16x16x32_bf16 v[16:19], v[168:171], v[216:219], v[16:19]
	v_mfma_f32_16x16x32_bf16 v[24:27], v[176:179], v[216:219], v[24:27]
	v_mfma_f32_16x16x32_bf16 v[56:59], v[172:175], v[192:195], v[56:59]
	v_mfma_f32_16x16x32_bf16 v[60:63], v[180:183], v[192:195], v[60:63]
	v_mfma_f32_16x16x32_bf16 v[48:51], v[172:175], v[204:207], v[48:51]
	v_mfma_f32_16x16x32_bf16 v[52:55], v[180:183], v[204:207], v[52:55]
	v_mfma_f32_16x16x32_bf16 v[32:35], v[172:175], v[212:215], v[32:35]
	v_mfma_f32_16x16x32_bf16 v[40:43], v[180:183], v[212:215], v[40:43]
	s_setprio 2
	s_barrier
	v_mfma_f32_16x16x32_bf16 v[16:19], v[172:175], v[220:223], v[16:19]
	v_mfma_f32_16x16x32_bf16 v[24:27], v[180:183], v[220:223], v[24:27]
	s_setprio 0
	v_add_u32_e32 v151, s50, v149
	ds_read_b128 v[152:155], v151
	ds_read_b128 v[156:159], v151 offset:1024
	ds_read_b128 v[160:163], v151 offset:2048
	ds_read_b128 v[164:167], v151 offset:3072
	v_add_u32_e32 v151, s51, v149
	ds_read_b128 v[168:171], v151
	ds_read_b128 v[172:175], v151 offset:1024
	ds_read_b128 v[176:179], v151 offset:2048
	ds_read_b128 v[180:183], v151 offset:3072
	s_add_u32 s78, s78, 0x4000
	s_addc_u32 s79, s79, 0
	s_mov_b32 m0, s43
	ds_read_b128 v[184:187], v150 offset:32768
	ds_read_b128 v[192:195], v150 offset:33792
	ds_read_b128 v[200:203], v150 offset:34816
	ds_read_b128 v[204:207], v150 offset:35840
	ds_read_b128 v[208:211], v150 offset:36864
	ds_read_b128 v[212:215], v150 offset:37888
	ds_read_b128 v[216:219], v150 offset:38912
	ds_read_b128 v[220:223], v150 offset:39936
	global_load_lds_dwordx4 v128, s[78:79] sc1
	s_mov_b32 m0, s44
	s_nop 0
	global_load_lds_dwordx4 v130, s[78:79] sc1
	s_waitcnt vmcnt(8)
	s_waitcnt lgkmcnt(0)
	s_setprio 1
	s_barrier
	v_mfma_f32_16x16x32_bf16 v[104:107], v[152:155], v[184:187], v[104:107]
	v_mfma_f32_16x16x32_bf16 v[108:111], v[160:163], v[184:187], v[108:111]
	v_mfma_f32_16x16x32_bf16 v[84:87], v[152:155], v[200:203], v[84:87]
	v_mfma_f32_16x16x32_bf16 v[92:95], v[160:163], v[200:203], v[92:95]
	v_mfma_f32_16x16x32_bf16 v[72:75], v[152:155], v[208:211], v[72:75]
	v_mfma_f32_16x16x32_bf16 v[76:79], v[160:163], v[208:211], v[76:79]
	v_mfma_f32_16x16x32_bf16 v[64:67], v[152:155], v[216:219], v[64:67]
	v_mfma_f32_16x16x32_bf16 v[68:71], v[160:163], v[216:219], v[68:71]
	v_mfma_f32_16x16x32_bf16 v[104:107], v[156:159], v[192:195], v[104:107]
	v_mfma_f32_16x16x32_bf16 v[108:111], v[164:167], v[192:195], v[108:111]
	v_mfma_f32_16x16x32_bf16 v[84:87], v[156:159], v[204:207], v[84:87]
	v_mfma_f32_16x16x32_bf16 v[92:95], v[164:167], v[204:207], v[92:95]
	v_mfma_f32_16x16x32_bf16 v[72:75], v[156:159], v[212:215], v[72:75]
	v_mfma_f32_16x16x32_bf16 v[76:79], v[164:167], v[212:215], v[76:79]
	v_mfma_f32_16x16x32_bf16 v[64:67], v[156:159], v[220:223], v[64:67]
	v_mfma_f32_16x16x32_bf16 v[68:71], v[164:167], v[220:223], v[68:71]
	v_mfma_f32_16x16x32_bf16 v[120:123], v[168:171], v[184:187], v[120:123]
	v_mfma_f32_16x16x32_bf16 v[124:127], v[176:179], v[184:187], v[124:127]
	v_mfma_f32_16x16x32_bf16 v[112:115], v[168:171], v[200:203], v[112:115]
	v_mfma_f32_16x16x32_bf16 v[116:119], v[176:179], v[200:203], v[116:119]
	v_mfma_f32_16x16x32_bf16 v[96:99], v[168:171], v[208:211], v[96:99]
	v_mfma_f32_16x16x32_bf16 v[100:103], v[176:179], v[208:211], v[100:103]
	v_mfma_f32_16x16x32_bf16 v[80:83], v[168:171], v[216:219], v[80:83]
	v_mfma_f32_16x16x32_bf16 v[88:91], v[176:179], v[216:219], v[88:91]
	v_mfma_f32_16x16x32_bf16 v[120:123], v[172:175], v[192:195], v[120:123]
	v_mfma_f32_16x16x32_bf16 v[124:127], v[180:183], v[192:195], v[124:127]
	v_mfma_f32_16x16x32_bf16 v[112:115], v[172:175], v[204:207], v[112:115]
	v_mfma_f32_16x16x32_bf16 v[116:119], v[180:183], v[204:207], v[116:119]
	v_mfma_f32_16x16x32_bf16 v[96:99], v[172:175], v[212:215], v[96:99]
	v_mfma_f32_16x16x32_bf16 v[100:103], v[180:183], v[212:215], v[100:103]
	s_setprio 2
	s_barrier
	v_mfma_f32_16x16x32_bf16 v[80:83], v[172:175], v[220:223], v[80:83]
	v_mfma_f32_16x16x32_bf16 v[88:91], v[180:183], v[220:223], v[88:91]
	s_setprio 0
	s_add_u32 s78, s70, 0x8000
	s_addc_u32 s79, s71, 0
	s_add_i32 s86, s50, s37
	s_mov_b32 m0, s86
	ds_read_b128 v[184:187], v150 offset:49152
	ds_read_b128 v[192:195], v150 offset:50176
	ds_read_b128 v[200:203], v150 offset:51200
	ds_read_b128 v[204:207], v150 offset:52224
	ds_read_b128 v[208:211], v150 offset:53248
	ds_read_b128 v[212:215], v150 offset:54272
	ds_read_b128 v[216:219], v150 offset:55296
	ds_read_b128 v[220:223], v150 offset:56320
	global_load_lds_dwordx4 v132, s[78:79] sc1
	s_add_i32 m0, s86, 0x2000
	s_add_u32 s70, s70, 0xc000
	global_load_lds_dwordx4 v134, s[78:79] sc1
	s_addc_u32 s71, s71, 0
	s_add_i32 s78, s51, s37
	s_mov_b32 m0, s78
	s_nop 0
	global_load_lds_dwordx4 v132, s[70:71] sc1
	s_add_i32 m0, s78, 0x2000
	s_nop 0
	global_load_lds_dwordx4 v134, s[70:71] sc1
	s_mov_b32 m0, s17
	s_nop 0
	global_load_lds_dwordx4 v128, s[66:67] sc1
	s_mov_b32 m0, s46
	s_nop 0
	global_load_lds_dwordx4 v130, s[66:67] sc1
	s_waitcnt vmcnt(8)
	s_waitcnt lgkmcnt(0)
	s_setprio 1
	s_barrier
	v_mfma_f32_16x16x32_bf16 v[36:39], v[152:155], v[184:187], v[36:39]
	v_mfma_f32_16x16x32_bf16 v[44:47], v[160:163], v[184:187], v[44:47]
	v_mfma_f32_16x16x32_bf16 v[20:23], v[152:155], v[200:203], v[20:23]
	v_mfma_f32_16x16x32_bf16 v[28:31], v[160:163], v[200:203], v[28:31]
	v_mfma_f32_16x16x32_bf16 v[8:11], v[152:155], v[208:211], v[8:11]
	v_mfma_f32_16x16x32_bf16 v[12:15], v[160:163], v[208:211], v[12:15]
	v_mfma_f32_16x16x32_bf16 v[0:3], v[152:155], v[216:219], v[0:3]
	v_mfma_f32_16x16x32_bf16 v[4:7], v[160:163], v[216:219], v[4:7]
	v_mfma_f32_16x16x32_bf16 v[36:39], v[156:159], v[192:195], v[36:39]
	v_mfma_f32_16x16x32_bf16 v[44:47], v[164:167], v[192:195], v[44:47]
	v_mfma_f32_16x16x32_bf16 v[20:23], v[156:159], v[204:207], v[20:23]
	v_mfma_f32_16x16x32_bf16 v[28:31], v[164:167], v[204:207], v[28:31]
	v_mfma_f32_16x16x32_bf16 v[8:11], v[156:159], v[212:215], v[8:11]
	v_mfma_f32_16x16x32_bf16 v[12:15], v[164:167], v[212:215], v[12:15]
	v_mfma_f32_16x16x32_bf16 v[0:3], v[156:159], v[220:223], v[0:3]
	v_mfma_f32_16x16x32_bf16 v[4:7], v[164:167], v[220:223], v[4:7]
	v_mfma_f32_16x16x32_bf16 v[56:59], v[168:171], v[184:187], v[56:59]
	v_mfma_f32_16x16x32_bf16 v[60:63], v[176:179], v[184:187], v[60:63]
	v_mfma_f32_16x16x32_bf16 v[48:51], v[168:171], v[200:203], v[48:51]
	v_mfma_f32_16x16x32_bf16 v[52:55], v[176:179], v[200:203], v[52:55]
	v_mfma_f32_16x16x32_bf16 v[32:35], v[168:171], v[208:211], v[32:35]
	v_mfma_f32_16x16x32_bf16 v[40:43], v[176:179], v[208:211], v[40:43]
	v_mfma_f32_16x16x32_bf16 v[16:19], v[168:171], v[216:219], v[16:19]
	v_mfma_f32_16x16x32_bf16 v[24:27], v[176:179], v[216:219], v[24:27]
	v_mfma_f32_16x16x32_bf16 v[56:59], v[172:175], v[192:195], v[56:59]
	v_mfma_f32_16x16x32_bf16 v[60:63], v[180:183], v[192:195], v[60:63]
	v_mfma_f32_16x16x32_bf16 v[48:51], v[172:175], v[204:207], v[48:51]
	v_mfma_f32_16x16x32_bf16 v[52:55], v[180:183], v[204:207], v[52:55]
	v_mfma_f32_16x16x32_bf16 v[32:35], v[172:175], v[212:215], v[32:35]
	v_mfma_f32_16x16x32_bf16 v[40:43], v[180:183], v[212:215], v[40:43]
	s_setprio 2
	s_barrier
	v_mfma_f32_16x16x32_bf16 v[16:19], v[172:175], v[220:223], v[16:19]
	v_mfma_f32_16x16x32_bf16 v[24:27], v[180:183], v[220:223], v[24:27]
	s_setprio 0
	s_add_i32 s85, s85, 2
	s_add_u32 s64, s64, 0x10000
	s_addc_u32 s65, s65, 0
	s_cmp_gt_u32 s85, 13
	s_cbranch_scc0 .LBB0_976
	s_add_u32 s64, s55, 0xffff0000
	s_addc_u32 s65, s69, -1
	s_andn2_b64 vcc, exec, s[8:9]
	s_cbranch_vccnz .LBB0_967
	s_mov_b32 s16, s38
	s_mov_b32 s10, s40
	s_mov_b64 s[18:19], s[62:63]
	s_mov_b32 s47, s54
	v_mov_b64 v[104:105], 0
	v_mov_b64 v[106:107], 0
	v_mov_b64 v[108:109], 0
	v_mov_b64 v[110:111], 0
	v_mov_b64 v[84:85], 0
	v_mov_b64 v[86:87], 0
	v_mov_b64 v[92:93], 0
	v_mov_b64 v[94:95], 0
	v_mov_b64 v[72:73], 0
	v_mov_b64 v[74:75], 0
	v_mov_b64 v[76:77], 0
	v_mov_b64 v[78:79], 0
	v_mov_b64 v[64:65], 0
	v_mov_b64 v[66:67], 0
	v_mov_b64 v[68:69], 0
	v_mov_b64 v[70:71], 0
	v_mov_b64 v[120:121], 0
	v_mov_b64 v[122:123], 0
	v_mov_b64 v[124:125], 0
	v_mov_b64 v[126:127], 0
	v_mov_b64 v[112:113], 0
	v_mov_b64 v[114:115], 0
	v_mov_b64 v[116:117], 0
	v_mov_b64 v[118:119], 0
	v_mov_b64 v[96:97], 0
	v_mov_b64 v[98:99], 0
	v_mov_b64 v[100:101], 0
	v_mov_b64 v[102:103], 0
	v_mov_b64 v[80:81], 0
	v_mov_b64 v[82:83], 0
	v_mov_b64 v[88:89], 0
	v_mov_b64 v[90:91], 0
	v_mov_b64 v[36:37], 0
	v_mov_b64 v[38:39], 0
	v_mov_b64 v[44:45], 0
	v_mov_b64 v[46:47], 0
	v_mov_b64 v[20:21], 0
	v_mov_b64 v[22:23], 0
	v_mov_b64 v[28:29], 0
	v_mov_b64 v[30:31], 0
	v_mov_b64 v[8:9], 0
	v_mov_b64 v[10:11], 0
	v_mov_b64 v[12:13], 0
	v_mov_b64 v[14:15], 0
	v_mov_b64 v[0:1], 0
	v_mov_b64 v[2:3], 0
	v_mov_b64 v[4:5], 0
	v_mov_b64 v[6:7], 0
	v_mov_b64 v[56:57], 0
	v_mov_b64 v[58:59], 0
	v_mov_b64 v[60:61], 0
	v_mov_b64 v[62:63], 0
	v_mov_b64 v[48:49], 0
	v_mov_b64 v[50:51], 0
	v_mov_b64 v[52:53], 0
	v_mov_b64 v[54:55], 0
	v_mov_b64 v[32:33], 0
	v_mov_b64 v[34:35], 0
	v_mov_b64 v[40:41], 0
	v_mov_b64 v[42:43], 0
	v_mov_b64 v[16:17], 0
	v_mov_b64 v[18:19], 0
	v_mov_b64 v[24:25], 0
	v_mov_b64 v[26:27], 0
	s_andn2_b64 vcc, exec, s[6:7]
	s_cbranch_vccnz .LBB0_968

.LBB0_1029:
	s_add_u32 s41, s56, s10
	s_addc_u32 s65, s57, s11
	v_add_u32_e32 v168, s50, v151
	v_add_u32_e32 v184, s51, v151
	s_add_u32 s41, s41, 0x10000
	ds_read_b128 v[156:159], v168
	ds_read_b128 v[160:163], v168 offset:1024
	ds_read_b128 v[164:167], v168 offset:2048
	ds_read_b128 v[168:171], v168 offset:3072
	ds_read_b128 v[172:175], v184
	ds_read_b128 v[176:179], v184 offset:1024
	ds_read_b128 v[180:183], v184 offset:2048
	ds_read_b128 v[184:187], v184 offset:3072
	s_addc_u32 s65, s65, 0
	s_add_u32 s70, s77, s10
	s_addc_u32 s71, s82, s11
	s_cmp_eq_u32 s10, 0x70000
	s_cselect_b32 s80, s84, s41
	s_cselect_b32 s81, s83, s65
	s_cselect_b32 s78, s86, s70
	s_cselect_b32 s79, s85, s71
	s_add_u32 s70, s80, 0x8000
	s_addc_u32 s71, s81, 0
	s_add_i32 s41, s42, 0xc000
	v_lshl_add_u64 v[196:197], v[144:145], 0, s[10:11]
	s_mov_b32 m0, s41
	s_add_i32 s65, s42, 0xe000
	ds_read_b128 v[192:195], v154
	ds_read_b128 v[200:203], v154 offset:1024
	ds_read_b128 v[204:207], v154 offset:2048
	ds_read_b128 v[208:211], v154 offset:3072
	ds_read_b128 v[212:215], v154 offset:4096
	ds_read_b128 v[216:219], v154 offset:5120
	ds_read_b128 v[220:223], v154 offset:6144
	ds_read_b128 v[224:227], v154 offset:7168
	global_load_lds_dwordx4 v[196:197], off sc1
	v_lshl_add_u64 v[196:197], v[146:147], 0, s[10:11]
	s_mov_b32 m0, s65
	s_nop 0
	global_load_lds_dwordx4 v[196:197], off sc1
	s_waitcnt vmcnt(8)
	s_waitcnt lgkmcnt(0)
	s_setprio 1
	s_barrier
	v_mfma_f32_16x16x32_bf16 v[112:115], v[156:159], v[192:195], v[112:115]
	v_mfma_f32_16x16x32_bf16 v[116:119], v[164:167], v[192:195], v[116:119]
	v_mfma_f32_16x16x32_bf16 v[96:99], v[156:159], v[204:207], v[96:99]
	v_mfma_f32_16x16x32_bf16 v[100:103], v[164:167], v[204:207], v[100:103]
	v_mfma_f32_16x16x32_bf16 v[80:83], v[156:159], v[212:215], v[80:83]
	v_mfma_f32_16x16x32_bf16 v[84:87], v[164:167], v[212:215], v[84:87]
	v_mfma_f32_16x16x32_bf16 v[64:67], v[156:159], v[220:223], v[64:67]
	v_mfma_f32_16x16x32_bf16 v[68:71], v[164:167], v[220:223], v[68:71]
	v_mfma_f32_16x16x32_bf16 v[112:115], v[160:163], v[200:203], v[112:115]
	v_mfma_f32_16x16x32_bf16 v[116:119], v[168:171], v[200:203], v[116:119]
	v_mfma_f32_16x16x32_bf16 v[96:99], v[160:163], v[208:211], v[96:99]
	v_mfma_f32_16x16x32_bf16 v[100:103], v[168:171], v[208:211], v[100:103]
	v_mfma_f32_16x16x32_bf16 v[80:83], v[160:163], v[216:219], v[80:83]
	v_mfma_f32_16x16x32_bf16 v[84:87], v[168:171], v[216:219], v[84:87]
	v_mfma_f32_16x16x32_bf16 v[64:67], v[160:163], v[224:227], v[64:67]
	v_mfma_f32_16x16x32_bf16 v[68:71], v[168:171], v[224:227], v[68:71]
	v_mfma_f32_16x16x32_bf16 v[120:123], v[172:175], v[192:195], v[120:123]
	v_mfma_f32_16x16x32_bf16 v[124:127], v[180:183], v[192:195], v[124:127]
	v_mfma_f32_16x16x32_bf16 v[104:107], v[172:175], v[204:207], v[104:107]
	v_mfma_f32_16x16x32_bf16 v[108:111], v[180:183], v[204:207], v[108:111]
	v_mfma_f32_16x16x32_bf16 v[88:91], v[172:175], v[212:215], v[88:91]
	v_mfma_f32_16x16x32_bf16 v[92:95], v[180:183], v[212:215], v[92:95]
	v_mfma_f32_16x16x32_bf16 v[72:75], v[172:175], v[220:223], v[72:75]
	v_mfma_f32_16x16x32_bf16 v[76:79], v[180:183], v[220:223], v[76:79]
	v_mfma_f32_16x16x32_bf16 v[120:123], v[176:179], v[200:203], v[120:123]
	v_mfma_f32_16x16x32_bf16 v[124:127], v[184:187], v[200:203], v[124:127]
	v_mfma_f32_16x16x32_bf16 v[104:107], v[176:179], v[208:211], v[104:107]
	v_mfma_f32_16x16x32_bf16 v[108:111], v[184:187], v[208:211], v[108:111]
	v_mfma_f32_16x16x32_bf16 v[88:91], v[176:179], v[216:219], v[88:91]
	v_mfma_f32_16x16x32_bf16 v[92:95], v[184:187], v[216:219], v[92:95]
	s_setprio 2
	s_barrier
	v_mfma_f32_16x16x32_bf16 v[72:75], v[176:179], v[224:227], v[72:75]
	v_mfma_f32_16x16x32_bf16 v[76:79], v[184:187], v[224:227], v[76:79]
	s_setprio 0
	s_add_i32 s88, s50, s35
	s_mov_b32 m0, s88
	ds_read_b128 v[192:195], v154 offset:16384
	ds_read_b128 v[200:203], v154 offset:17408
	ds_read_b128 v[204:207], v154 offset:18432
	ds_read_b128 v[208:211], v154 offset:19456
	ds_read_b128 v[212:215], v154 offset:20480
	ds_read_b128 v[216:219], v154 offset:21504
	ds_read_b128 v[220:223], v154 offset:22528
	ds_read_b128 v[224:227], v154 offset:23552
	global_load_lds_dwordx4 v132, s[78:79] sc1
	s_add_i32 m0, s88, 0x2000
	s_add_u32 s88, s78, 0x4000
	s_addc_u32 s89, s79, 0
	s_add_i32 s90, s51, s35
	global_load_lds_dwordx4 v134, s[78:79] sc1
	s_mov_b32 m0, s90
	s_nop 0
	global_load_lds_dwordx4 v132, s[88:89] sc1
	s_add_i32 m0, s90, 0x2000
	s_nop 0
	global_load_lds_dwordx4 v134, s[88:89] sc1
	s_mov_b32 m0, s42
	s_nop 0
	global_load_lds_dwordx4 v128, s[80:81] sc1
	s_mov_b32 m0, s43
	s_nop 0
	global_load_lds_dwordx4 v130, s[80:81] sc1
	s_waitcnt vmcnt(8)
	s_waitcnt lgkmcnt(0)
	s_setprio 1
	s_barrier
	v_mfma_f32_16x16x32_bf16 v[48:51], v[156:159], v[192:195], v[48:51]
	v_mfma_f32_16x16x32_bf16 v[52:55], v[164:167], v[192:195], v[52:55]
	v_mfma_f32_16x16x32_bf16 v[32:35], v[156:159], v[204:207], v[32:35]
	v_mfma_f32_16x16x32_bf16 v[36:39], v[164:167], v[204:207], v[36:39]
	v_mfma_f32_16x16x32_bf16 v[16:19], v[156:159], v[212:215], v[16:19]
	v_mfma_f32_16x16x32_bf16 v[20:23], v[164:167], v[212:215], v[20:23]
	v_mfma_f32_16x16x32_bf16 v[0:3], v[156:159], v[220:223], v[0:3]
	v_mfma_f32_16x16x32_bf16 v[4:7], v[164:167], v[220:223], v[4:7]
	v_mfma_f32_16x16x32_bf16 v[48:51], v[160:163], v[200:203], v[48:51]
	v_mfma_f32_16x16x32_bf16 v[52:55], v[168:171], v[200:203], v[52:55]
	v_mfma_f32_16x16x32_bf16 v[32:35], v[160:163], v[208:211], v[32:35]
	v_mfma_f32_16x16x32_bf16 v[36:39], v[168:171], v[208:211], v[36:39]
	v_mfma_f32_16x16x32_bf16 v[16:19], v[160:163], v[216:219], v[16:19]
	v_mfma_f32_16x16x32_bf16 v[20:23], v[168:171], v[216:219], v[20:23]
	v_mfma_f32_16x16x32_bf16 v[0:3], v[160:163], v[224:227], v[0:3]
	v_mfma_f32_16x16x32_bf16 v[4:7], v[168:171], v[224:227], v[4:7]
	v_mfma_f32_16x16x32_bf16 v[56:59], v[172:175], v[192:195], v[56:59]
	v_mfma_f32_16x16x32_bf16 v[60:63], v[180:183], v[192:195], v[60:63]
	v_mfma_f32_16x16x32_bf16 v[40:43], v[172:175], v[204:207], v[40:43]
	v_mfma_f32_16x16x32_bf16 v[44:47], v[180:183], v[204:207], v[44:47]
	v_mfma_f32_16x16x32_bf16 v[24:27], v[172:175], v[212:215], v[24:27]
	v_mfma_f32_16x16x32_bf16 v[28:31], v[180:183], v[212:215], v[28:31]
	v_mfma_f32_16x16x32_bf16 v[8:11], v[172:175], v[220:223], v[8:11]
	v_mfma_f32_16x16x32_bf16 v[12:15], v[180:183], v[220:223], v[12:15]
	v_mfma_f32_16x16x32_bf16 v[56:59], v[176:179], v[200:203], v[56:59]
	v_mfma_f32_16x16x32_bf16 v[60:63], v[184:187], v[200:203], v[60:63]
	v_mfma_f32_16x16x32_bf16 v[40:43], v[176:179], v[208:211], v[40:43]
	v_mfma_f32_16x16x32_bf16 v[44:47], v[184:187], v[208:211], v[44:47]
	v_mfma_f32_16x16x32_bf16 v[24:27], v[176:179], v[216:219], v[24:27]
	v_mfma_f32_16x16x32_bf16 v[28:31], v[184:187], v[216:219], v[28:31]
	s_setprio 2
	s_barrier
	v_mfma_f32_16x16x32_bf16 v[8:11], v[176:179], v[224:227], v[8:11]
	v_mfma_f32_16x16x32_bf16 v[12:15], v[184:187], v[224:227], v[12:15]
	s_setprio 0
	v_add_u32_e32 v168, s54, v151
	v_add_u32_e32 v184, s55, v151
	ds_read_b128 v[156:159], v168
	ds_read_b128 v[160:163], v168 offset:1024
	ds_read_b128 v[164:167], v168 offset:2048
	ds_read_b128 v[168:171], v168 offset:3072
	ds_read_b128 v[172:175], v184
	ds_read_b128 v[176:179], v184 offset:1024
	ds_read_b128 v[180:183], v184 offset:2048
	ds_read_b128 v[184:187], v184 offset:3072
	s_add_u32 s80, s80, 0x4000
	s_addc_u32 s81, s81, 0
	s_mov_b32 m0, s44
	ds_read_b128 v[192:195], v154 offset:32768
	ds_read_b128 v[200:203], v154 offset:33792
	ds_read_b128 v[204:207], v154 offset:34816
	ds_read_b128 v[208:211], v154 offset:35840
	ds_read_b128 v[212:215], v154 offset:36864
	ds_read_b128 v[216:219], v154 offset:37888
	ds_read_b128 v[220:223], v154 offset:38912
	ds_read_b128 v[224:227], v154 offset:39936
	global_load_lds_dwordx4 v128, s[80:81] sc1
	s_mov_b32 m0, s45
	s_nop 0
	global_load_lds_dwordx4 v130, s[80:81] sc1
	s_waitcnt vmcnt(8)
	s_waitcnt lgkmcnt(0)
	s_setprio 1
	s_barrier
	v_mfma_f32_16x16x32_bf16 v[112:115], v[156:159], v[192:195], v[112:115]
	v_mfma_f32_16x16x32_bf16 v[116:119], v[164:167], v[192:195], v[116:119]
	v_mfma_f32_16x16x32_bf16 v[96:99], v[156:159], v[204:207], v[96:99]
	v_mfma_f32_16x16x32_bf16 v[100:103], v[164:167], v[204:207], v[100:103]
	v_mfma_f32_16x16x32_bf16 v[80:83], v[156:159], v[212:215], v[80:83]
	v_mfma_f32_16x16x32_bf16 v[84:87], v[164:167], v[212:215], v[84:87]
	v_mfma_f32_16x16x32_bf16 v[64:67], v[156:159], v[220:223], v[64:67]
	v_mfma_f32_16x16x32_bf16 v[68:71], v[164:167], v[220:223], v[68:71]
	v_mfma_f32_16x16x32_bf16 v[112:115], v[160:163], v[200:203], v[112:115]
	v_mfma_f32_16x16x32_bf16 v[116:119], v[168:171], v[200:203], v[116:119]
	v_mfma_f32_16x16x32_bf16 v[96:99], v[160:163], v[208:211], v[96:99]
	v_mfma_f32_16x16x32_bf16 v[100:103], v[168:171], v[208:211], v[100:103]
	v_mfma_f32_16x16x32_bf16 v[80:83], v[160:163], v[216:219], v[80:83]
	v_mfma_f32_16x16x32_bf16 v[84:87], v[168:171], v[216:219], v[84:87]
	v_mfma_f32_16x16x32_bf16 v[64:67], v[160:163], v[224:227], v[64:67]
	v_mfma_f32_16x16x32_bf16 v[68:71], v[168:171], v[224:227], v[68:71]
	v_mfma_f32_16x16x32_bf16 v[120:123], v[172:175], v[192:195], v[120:123]
	v_mfma_f32_16x16x32_bf16 v[124:127], v[180:183], v[192:195], v[124:127]
	v_mfma_f32_16x16x32_bf16 v[104:107], v[172:175], v[204:207], v[104:107]
	v_mfma_f32_16x16x32_bf16 v[108:111], v[180:183], v[204:207], v[108:111]
	v_mfma_f32_16x16x32_bf16 v[88:91], v[172:175], v[212:215], v[88:91]
	v_mfma_f32_16x16x32_bf16 v[92:95], v[180:183], v[212:215], v[92:95]
	v_mfma_f32_16x16x32_bf16 v[72:75], v[172:175], v[220:223], v[72:75]
	v_mfma_f32_16x16x32_bf16 v[76:79], v[180:183], v[220:223], v[76:79]
	v_mfma_f32_16x16x32_bf16 v[120:123], v[176:179], v[200:203], v[120:123]
	v_mfma_f32_16x16x32_bf16 v[124:127], v[184:187], v[200:203], v[124:127]
	v_mfma_f32_16x16x32_bf16 v[104:107], v[176:179], v[208:211], v[104:107]
	v_mfma_f32_16x16x32_bf16 v[108:111], v[184:187], v[208:211], v[108:111]
	v_mfma_f32_16x16x32_bf16 v[88:91], v[176:179], v[216:219], v[88:91]
	v_mfma_f32_16x16x32_bf16 v[92:95], v[184:187], v[216:219], v[92:95]
	s_setprio 2
	s_barrier
	v_mfma_f32_16x16x32_bf16 v[72:75], v[176:179], v[224:227], v[72:75]
	v_mfma_f32_16x16x32_bf16 v[76:79], v[184:187], v[224:227], v[76:79]
	s_setprio 0
	s_add_u32 s80, s78, 0x8000
	s_addc_u32 s81, s79, 0
	s_add_i32 s88, s54, s35
	s_mov_b32 m0, s88
	ds_read_b128 v[192:195], v154 offset:49152
	ds_read_b128 v[200:203], v154 offset:50176
	ds_read_b128 v[204:207], v154 offset:51200
	ds_read_b128 v[208:211], v154 offset:52224
	ds_read_b128 v[212:215], v154 offset:53248
	ds_read_b128 v[216:219], v154 offset:54272
	ds_read_b128 v[220:223], v154 offset:55296
	ds_read_b128 v[224:227], v154 offset:56320
	global_load_lds_dwordx4 v132, s[80:81] sc1
	s_add_i32 m0, s88, 0x2000
	s_add_u32 s78, s78, 0xc000
	global_load_lds_dwordx4 v134, s[80:81] sc1
	s_addc_u32 s79, s79, 0
	s_add_i32 s80, s55, s35
	s_mov_b32 m0, s80
	s_nop 0
	global_load_lds_dwordx4 v132, s[78:79] sc1
	s_add_i32 m0, s80, 0x2000
	s_nop 0
	global_load_lds_dwordx4 v134, s[78:79] sc1
	s_mov_b32 m0, s47
	s_nop 0
	global_load_lds_dwordx4 v128, s[70:71] sc1
	s_mov_b32 m0, s48
	s_nop 0
	global_load_lds_dwordx4 v130, s[70:71] sc1
	s_waitcnt vmcnt(8)
	s_waitcnt lgkmcnt(0)
	s_setprio 1
	s_barrier
	v_mfma_f32_16x16x32_bf16 v[48:51], v[156:159], v[192:195], v[48:51]
	v_mfma_f32_16x16x32_bf16 v[52:55], v[164:167], v[192:195], v[52:55]
	v_mfma_f32_16x16x32_bf16 v[32:35], v[156:159], v[204:207], v[32:35]
	v_mfma_f32_16x16x32_bf16 v[36:39], v[164:167], v[204:207], v[36:39]
	v_mfma_f32_16x16x32_bf16 v[16:19], v[156:159], v[212:215], v[16:19]
	v_mfma_f32_16x16x32_bf16 v[20:23], v[164:167], v[212:215], v[20:23]
	v_mfma_f32_16x16x32_bf16 v[0:3], v[156:159], v[220:223], v[0:3]
	v_mfma_f32_16x16x32_bf16 v[4:7], v[164:167], v[220:223], v[4:7]
	v_mfma_f32_16x16x32_bf16 v[48:51], v[160:163], v[200:203], v[48:51]
	v_mfma_f32_16x16x32_bf16 v[52:55], v[168:171], v[200:203], v[52:55]
	v_mfma_f32_16x16x32_bf16 v[32:35], v[160:163], v[208:211], v[32:35]
	v_mfma_f32_16x16x32_bf16 v[36:39], v[168:171], v[208:211], v[36:39]
	v_mfma_f32_16x16x32_bf16 v[16:19], v[160:163], v[216:219], v[16:19]
	v_mfma_f32_16x16x32_bf16 v[20:23], v[168:171], v[216:219], v[20:23]
	v_mfma_f32_16x16x32_bf16 v[0:3], v[160:163], v[224:227], v[0:3]
	v_mfma_f32_16x16x32_bf16 v[4:7], v[168:171], v[224:227], v[4:7]
	v_mfma_f32_16x16x32_bf16 v[56:59], v[172:175], v[192:195], v[56:59]
	v_mfma_f32_16x16x32_bf16 v[60:63], v[180:183], v[192:195], v[60:63]
	v_mfma_f32_16x16x32_bf16 v[40:43], v[172:175], v[204:207], v[40:43]
	v_mfma_f32_16x16x32_bf16 v[44:47], v[180:183], v[204:207], v[44:47]
	v_mfma_f32_16x16x32_bf16 v[24:27], v[172:175], v[212:215], v[24:27]
	v_mfma_f32_16x16x32_bf16 v[28:31], v[180:183], v[212:215], v[28:31]
	v_mfma_f32_16x16x32_bf16 v[8:11], v[172:175], v[220:223], v[8:11]
	v_mfma_f32_16x16x32_bf16 v[12:15], v[180:183], v[220:223], v[12:15]
	v_mfma_f32_16x16x32_bf16 v[56:59], v[176:179], v[200:203], v[56:59]
	v_mfma_f32_16x16x32_bf16 v[60:63], v[184:187], v[200:203], v[60:63]
	v_mfma_f32_16x16x32_bf16 v[40:43], v[176:179], v[208:211], v[40:43]
	v_mfma_f32_16x16x32_bf16 v[44:47], v[184:187], v[208:211], v[44:47]
	v_mfma_f32_16x16x32_bf16 v[24:27], v[176:179], v[216:219], v[24:27]
	v_mfma_f32_16x16x32_bf16 v[28:31], v[184:187], v[216:219], v[28:31]
	s_setprio 2
	s_barrier
	v_mfma_f32_16x16x32_bf16 v[8:11], v[176:179], v[224:227], v[8:11]
	v_mfma_f32_16x16x32_bf16 v[12:15], v[184:187], v[224:227], v[12:15]
	s_setprio 0
	s_add_i32 s87, s87, 2
	s_add_u32 s10, s10, 0x10000
	s_addc_u32 s11, s11, 0
	s_cmp_gt_u32 s87, 13
	s_cbranch_scc0 .LBB0_1029
	s_add_u32 s10, s77, 0xffff0000
	s_addc_u32 s11, s82, -1
	s_and_b64 vcc, exec, s[8:9]
	s_cbranch_vccz .LBB0_1019
	s_mov_b64 s[62:63], s[10:11]
	s_andn2_b64 vcc, exec, s[6:7]
	s_cbranch_vccnz .LBB0_1020

.LBB0_1093:
	v_add_u32_e32 v155, s47, v148
	ds_read_b128 v[156:159], v155
	ds_read_b128 v[160:163], v155 offset:1024
	ds_read_b128 v[164:167], v155 offset:2048
	ds_read_b128 v[168:171], v155 offset:3072
	v_add_u32_e32 v155, s48, v148
	ds_read_b128 v[172:175], v155
	ds_read_b128 v[176:179], v155 offset:1024
	ds_read_b128 v[180:183], v155 offset:2048
	ds_read_b128 v[184:187], v155 offset:3072
	s_add_u32 s40, s18, 0x10000
	s_addc_u32 s41, s19, 0
	s_cmp_eq_u32 s78, 12
	s_cselect_b32 s64, s69, s40
	s_cselect_b32 s65, s55, s41
	s_cselect_b32 s62, s71, s76
	s_cselect_b32 s63, s70, s77
	s_add_u32 s56, s64, 0x8000
	s_addc_u32 s57, s65, 0
	s_add_i32 m0, s37, 0xc000
	ds_read_b128 v[192:195], v154
	ds_read_b128 v[200:203], v154 offset:1024
	ds_read_b128 v[204:207], v154 offset:2048
	ds_read_b128 v[208:211], v154 offset:3072
	ds_read_b128 v[212:215], v154 offset:4096
	ds_read_b128 v[216:219], v154 offset:5120
	ds_read_b128 v[220:223], v154 offset:6144
	ds_read_b128 v[224:227], v154 offset:7168
	global_load_lds_dwordx4 v144, s[18:19] sc1
	s_add_i32 m0, s37, 0xe000
	s_nop 0
	global_load_lds_dwordx4 v146, s[18:19] sc1
	s_waitcnt vmcnt(8)
	s_waitcnt lgkmcnt(0)
	s_setprio 1
	s_barrier
	v_mfma_f32_16x16x32_bf16 v[116:119], v[156:159], v[192:195], v[116:119]
	v_mfma_f32_16x16x32_bf16 v[108:111], v[164:167], v[192:195], v[108:111]
	v_mfma_f32_16x16x32_bf16 v[100:103], v[156:159], v[204:207], v[100:103]
	v_mfma_f32_16x16x32_bf16 v[92:95], v[164:167], v[204:207], v[92:95]
	v_mfma_f32_16x16x32_bf16 v[84:87], v[156:159], v[212:215], v[84:87]
	v_mfma_f32_16x16x32_bf16 v[76:79], v[164:167], v[212:215], v[76:79]
	v_mfma_f32_16x16x32_bf16 v[60:63], v[156:159], v[220:223], v[60:63]
	v_mfma_f32_16x16x32_bf16 v[52:55], v[164:167], v[220:223], v[52:55]
	v_mfma_f32_16x16x32_bf16 v[116:119], v[160:163], v[200:203], v[116:119]
	v_mfma_f32_16x16x32_bf16 v[108:111], v[168:171], v[200:203], v[108:111]
	v_mfma_f32_16x16x32_bf16 v[100:103], v[160:163], v[208:211], v[100:103]
	v_mfma_f32_16x16x32_bf16 v[92:95], v[168:171], v[208:211], v[92:95]
	v_mfma_f32_16x16x32_bf16 v[84:87], v[160:163], v[216:219], v[84:87]
	v_mfma_f32_16x16x32_bf16 v[76:79], v[168:171], v[216:219], v[76:79]
	v_mfma_f32_16x16x32_bf16 v[60:63], v[160:163], v[224:227], v[60:63]
	v_mfma_f32_16x16x32_bf16 v[52:55], v[168:171], v[224:227], v[52:55]
	v_mfma_f32_16x16x32_bf16 v[124:127], v[172:175], v[192:195], v[124:127]
	v_mfma_f32_16x16x32_bf16 v[120:123], v[180:183], v[192:195], v[120:123]
	v_mfma_f32_16x16x32_bf16 v[112:115], v[172:175], v[204:207], v[112:115]
	v_mfma_f32_16x16x32_bf16 v[104:107], v[180:183], v[204:207], v[104:107]
	v_mfma_f32_16x16x32_bf16 v[96:99], v[172:175], v[212:215], v[96:99]
	v_mfma_f32_16x16x32_bf16 v[88:91], v[180:183], v[212:215], v[88:91]
	v_mfma_f32_16x16x32_bf16 v[80:83], v[172:175], v[220:223], v[80:83]
	v_mfma_f32_16x16x32_bf16 v[68:71], v[180:183], v[220:223], v[68:71]
	v_mfma_f32_16x16x32_bf16 v[124:127], v[176:179], v[200:203], v[124:127]
	v_mfma_f32_16x16x32_bf16 v[120:123], v[184:187], v[200:203], v[120:123]
	v_mfma_f32_16x16x32_bf16 v[112:115], v[176:179], v[208:211], v[112:115]
	v_mfma_f32_16x16x32_bf16 v[104:107], v[184:187], v[208:211], v[104:107]
	v_mfma_f32_16x16x32_bf16 v[96:99], v[176:179], v[216:219], v[96:99]
	v_mfma_f32_16x16x32_bf16 v[88:91], v[184:187], v[216:219], v[88:91]
	s_setprio 2
	s_barrier
	v_mfma_f32_16x16x32_bf16 v[80:83], v[176:179], v[224:227], v[80:83]
	v_mfma_f32_16x16x32_bf16 v[68:71], v[184:187], v[224:227], v[68:71]
	s_setprio 0
	s_add_i32 s18, s47, s36
	s_mov_b32 m0, s18
	ds_read_b128 v[192:195], v154 offset:16384
	ds_read_b128 v[200:203], v154 offset:17408
	ds_read_b128 v[204:207], v154 offset:18432
	ds_read_b128 v[208:211], v154 offset:19456
	ds_read_b128 v[212:215], v154 offset:20480
	ds_read_b128 v[216:219], v154 offset:21504
	ds_read_b128 v[220:223], v154 offset:22528
	ds_read_b128 v[224:227], v154 offset:23552
	global_load_lds_dwordx4 v132, s[62:63] sc1
	s_add_i32 m0, s18, 0x2000
	s_add_u32 s18, s62, 0x4000
	s_addc_u32 s19, s63, 0
	s_add_i32 s79, s48, s36
	global_load_lds_dwordx4 v134, s[62:63] sc1
	s_mov_b32 m0, s79
	s_nop 0
	global_load_lds_dwordx4 v132, s[18:19] sc1
	s_add_i32 m0, s79, 0x2000
	s_nop 0
	global_load_lds_dwordx4 v134, s[18:19] sc1
	s_mov_b32 m0, s37
	s_nop 0
	global_load_lds_dwordx4 v130, s[64:65] sc1
	s_mov_b32 m0, s42
	s_nop 0
	global_load_lds_dwordx4 v128, s[64:65] sc1
	s_waitcnt vmcnt(8)
	s_waitcnt lgkmcnt(0)
	s_setprio 1
	s_barrier
	v_mfma_f32_16x16x32_bf16 v[56:59], v[156:159], v[192:195], v[56:59]
	v_mfma_f32_16x16x32_bf16 v[44:47], v[164:167], v[192:195], v[44:47]
	v_mfma_f32_16x16x32_bf16 v[36:39], v[156:159], v[204:207], v[36:39]
	v_mfma_f32_16x16x32_bf16 v[28:31], v[164:167], v[204:207], v[28:31]
	v_mfma_f32_16x16x32_bf16 v[20:23], v[156:159], v[212:215], v[20:23]
	v_mfma_f32_16x16x32_bf16 v[12:15], v[164:167], v[212:215], v[12:15]
	v_mfma_f32_16x16x32_bf16 v[4:7], v[156:159], v[220:223], v[4:7]
	v_mfma_f32_16x16x32_bf16 v[0:3], v[164:167], v[220:223], v[0:3]
	v_mfma_f32_16x16x32_bf16 v[56:59], v[160:163], v[200:203], v[56:59]
	v_mfma_f32_16x16x32_bf16 v[44:47], v[168:171], v[200:203], v[44:47]
	v_mfma_f32_16x16x32_bf16 v[36:39], v[160:163], v[208:211], v[36:39]
	v_mfma_f32_16x16x32_bf16 v[28:31], v[168:171], v[208:211], v[28:31]
	v_mfma_f32_16x16x32_bf16 v[20:23], v[160:163], v[216:219], v[20:23]
	v_mfma_f32_16x16x32_bf16 v[12:15], v[168:171], v[216:219], v[12:15]
	v_mfma_f32_16x16x32_bf16 v[4:7], v[160:163], v[224:227], v[4:7]
	v_mfma_f32_16x16x32_bf16 v[0:3], v[168:171], v[224:227], v[0:3]
	v_mfma_f32_16x16x32_bf16 v[72:75], v[172:175], v[192:195], v[72:75]
	v_mfma_f32_16x16x32_bf16 v[64:67], v[180:183], v[192:195], v[64:67]
	v_mfma_f32_16x16x32_bf16 v[48:51], v[172:175], v[204:207], v[48:51]
	v_mfma_f32_16x16x32_bf16 v[40:43], v[180:183], v[204:207], v[40:43]
	v_mfma_f32_16x16x32_bf16 v[32:35], v[172:175], v[212:215], v[32:35]
	v_mfma_f32_16x16x32_bf16 v[24:27], v[180:183], v[212:215], v[24:27]
	v_mfma_f32_16x16x32_bf16 v[16:19], v[172:175], v[220:223], v[16:19]
	v_mfma_f32_16x16x32_bf16 v[8:11], v[180:183], v[220:223], v[8:11]
	v_mfma_f32_16x16x32_bf16 v[72:75], v[176:179], v[200:203], v[72:75]
	v_mfma_f32_16x16x32_bf16 v[64:67], v[184:187], v[200:203], v[64:67]
	v_mfma_f32_16x16x32_bf16 v[48:51], v[176:179], v[208:211], v[48:51]
	v_mfma_f32_16x16x32_bf16 v[40:43], v[184:187], v[208:211], v[40:43]
	v_mfma_f32_16x16x32_bf16 v[32:35], v[176:179], v[216:219], v[32:35]
	v_mfma_f32_16x16x32_bf16 v[24:27], v[184:187], v[216:219], v[24:27]
	s_setprio 2
	s_barrier
	v_mfma_f32_16x16x32_bf16 v[16:19], v[176:179], v[224:227], v[16:19]
	v_mfma_f32_16x16x32_bf16 v[8:11], v[184:187], v[224:227], v[8:11]
	s_setprio 0
	v_add_u32_e32 v155, s49, v148
	ds_read_b128 v[156:159], v155
	ds_read_b128 v[160:163], v155 offset:1024
	ds_read_b128 v[164:167], v155 offset:2048
	ds_read_b128 v[168:171], v155 offset:3072
	v_add_u32_e32 v155, s50, v148
	ds_read_b128 v[172:175], v155
	ds_read_b128 v[176:179], v155 offset:1024
	ds_read_b128 v[180:183], v155 offset:2048
	ds_read_b128 v[184:187], v155 offset:3072
	s_add_u32 s18, s64, 0x4000
	s_addc_u32 s19, s65, 0
	s_mov_b32 m0, s43
	ds_read_b128 v[192:195], v154 offset:32768
	ds_read_b128 v[200:203], v154 offset:33792
	ds_read_b128 v[204:207], v154 offset:34816
	ds_read_b128 v[208:211], v154 offset:35840
	ds_read_b128 v[212:215], v154 offset:36864
	ds_read_b128 v[216:219], v154 offset:37888
	ds_read_b128 v[220:223], v154 offset:38912
	ds_read_b128 v[224:227], v154 offset:39936
	global_load_lds_dwordx4 v130, s[18:19] sc1
	s_mov_b32 m0, s44
	s_nop 0
	global_load_lds_dwordx4 v128, s[18:19] sc1
	s_waitcnt vmcnt(8)
	s_waitcnt lgkmcnt(0)
	s_setprio 1
	s_barrier
	v_mfma_f32_16x16x32_bf16 v[116:119], v[156:159], v[192:195], v[116:119]
	v_mfma_f32_16x16x32_bf16 v[108:111], v[164:167], v[192:195], v[108:111]
	v_mfma_f32_16x16x32_bf16 v[100:103], v[156:159], v[204:207], v[100:103]
	v_mfma_f32_16x16x32_bf16 v[92:95], v[164:167], v[204:207], v[92:95]
	v_mfma_f32_16x16x32_bf16 v[84:87], v[156:159], v[212:215], v[84:87]
	v_mfma_f32_16x16x32_bf16 v[76:79], v[164:167], v[212:215], v[76:79]
	v_mfma_f32_16x16x32_bf16 v[60:63], v[156:159], v[220:223], v[60:63]
	v_mfma_f32_16x16x32_bf16 v[52:55], v[164:167], v[220:223], v[52:55]
	v_mfma_f32_16x16x32_bf16 v[116:119], v[160:163], v[200:203], v[116:119]
	v_mfma_f32_16x16x32_bf16 v[108:111], v[168:171], v[200:203], v[108:111]
	v_mfma_f32_16x16x32_bf16 v[100:103], v[160:163], v[208:211], v[100:103]
	v_mfma_f32_16x16x32_bf16 v[92:95], v[168:171], v[208:211], v[92:95]
	v_mfma_f32_16x16x32_bf16 v[84:87], v[160:163], v[216:219], v[84:87]
	v_mfma_f32_16x16x32_bf16 v[76:79], v[168:171], v[216:219], v[76:79]
	v_mfma_f32_16x16x32_bf16 v[60:63], v[160:163], v[224:227], v[60:63]
	v_mfma_f32_16x16x32_bf16 v[52:55], v[168:171], v[224:227], v[52:55]
	v_mfma_f32_16x16x32_bf16 v[124:127], v[172:175], v[192:195], v[124:127]
	v_mfma_f32_16x16x32_bf16 v[120:123], v[180:183], v[192:195], v[120:123]
	v_mfma_f32_16x16x32_bf16 v[112:115], v[172:175], v[204:207], v[112:115]
	v_mfma_f32_16x16x32_bf16 v[104:107], v[180:183], v[204:207], v[104:107]
	v_mfma_f32_16x16x32_bf16 v[96:99], v[172:175], v[212:215], v[96:99]
	v_mfma_f32_16x16x32_bf16 v[88:91], v[180:183], v[212:215], v[88:91]
	v_mfma_f32_16x16x32_bf16 v[80:83], v[172:175], v[220:223], v[80:83]
	v_mfma_f32_16x16x32_bf16 v[68:71], v[180:183], v[220:223], v[68:71]
	v_mfma_f32_16x16x32_bf16 v[124:127], v[176:179], v[200:203], v[124:127]
	v_mfma_f32_16x16x32_bf16 v[120:123], v[184:187], v[200:203], v[120:123]
	v_mfma_f32_16x16x32_bf16 v[112:115], v[176:179], v[208:211], v[112:115]
	v_mfma_f32_16x16x32_bf16 v[104:107], v[184:187], v[208:211], v[104:107]
	v_mfma_f32_16x16x32_bf16 v[96:99], v[176:179], v[216:219], v[96:99]
	v_mfma_f32_16x16x32_bf16 v[88:91], v[184:187], v[216:219], v[88:91]
	s_setprio 2
	s_barrier
	v_mfma_f32_16x16x32_bf16 v[80:83], v[176:179], v[224:227], v[80:83]
	v_mfma_f32_16x16x32_bf16 v[68:71], v[184:187], v[224:227], v[68:71]
	s_setprio 0
	s_add_u32 s18, s62, 0x8000
	s_addc_u32 s19, s63, 0
	s_add_i32 s64, s49, s36
	s_mov_b32 m0, s64
	ds_read_b128 v[192:195], v154 offset:49152
	ds_read_b128 v[200:203], v154 offset:50176
	ds_read_b128 v[204:207], v154 offset:51200
	ds_read_b128 v[208:211], v154 offset:52224
	ds_read_b128 v[212:215], v154 offset:53248
	ds_read_b128 v[216:219], v154 offset:54272
	ds_read_b128 v[220:223], v154 offset:55296
	ds_read_b128 v[224:227], v154 offset:56320
	global_load_lds_dwordx4 v132, s[18:19] sc1
	s_add_i32 m0, s64, 0x2000
	s_nop 0
	global_load_lds_dwordx4 v134, s[18:19] sc1
	s_add_u32 s18, s62, 0xc000
	s_addc_u32 s19, s63, 0
	s_add_i32 s62, s50, s36
	s_mov_b32 m0, s62
	s_nop 0
	global_load_lds_dwordx4 v132, s[18:19] sc1
	s_add_i32 m0, s62, 0x2000
	s_nop 0
	global_load_lds_dwordx4 v134, s[18:19] sc1
	s_mov_b32 m0, s7
	s_nop 0
	global_load_lds_dwordx4 v130, s[56:57] sc1
	s_mov_b32 m0, s45
	s_nop 0
	global_load_lds_dwordx4 v128, s[56:57] sc1
	s_waitcnt vmcnt(8)
	s_waitcnt lgkmcnt(0)
	s_setprio 1
	s_barrier
	v_mfma_f32_16x16x32_bf16 v[56:59], v[156:159], v[192:195], v[56:59]
	v_mfma_f32_16x16x32_bf16 v[44:47], v[164:167], v[192:195], v[44:47]
	v_mfma_f32_16x16x32_bf16 v[36:39], v[156:159], v[204:207], v[36:39]
	v_mfma_f32_16x16x32_bf16 v[28:31], v[164:167], v[204:207], v[28:31]
	v_mfma_f32_16x16x32_bf16 v[20:23], v[156:159], v[212:215], v[20:23]
	v_mfma_f32_16x16x32_bf16 v[12:15], v[164:167], v[212:215], v[12:15]
	v_mfma_f32_16x16x32_bf16 v[4:7], v[156:159], v[220:223], v[4:7]
	v_mfma_f32_16x16x32_bf16 v[0:3], v[164:167], v[220:223], v[0:3]
	v_mfma_f32_16x16x32_bf16 v[56:59], v[160:163], v[200:203], v[56:59]
	v_mfma_f32_16x16x32_bf16 v[44:47], v[168:171], v[200:203], v[44:47]
	v_mfma_f32_16x16x32_bf16 v[36:39], v[160:163], v[208:211], v[36:39]
	v_mfma_f32_16x16x32_bf16 v[28:31], v[168:171], v[208:211], v[28:31]
	v_mfma_f32_16x16x32_bf16 v[20:23], v[160:163], v[216:219], v[20:23]
	v_mfma_f32_16x16x32_bf16 v[12:15], v[168:171], v[216:219], v[12:15]
	v_mfma_f32_16x16x32_bf16 v[4:7], v[160:163], v[224:227], v[4:7]
	v_mfma_f32_16x16x32_bf16 v[0:3], v[168:171], v[224:227], v[0:3]
	v_mfma_f32_16x16x32_bf16 v[72:75], v[172:175], v[192:195], v[72:75]
	v_mfma_f32_16x16x32_bf16 v[64:67], v[180:183], v[192:195], v[64:67]
	v_mfma_f32_16x16x32_bf16 v[48:51], v[172:175], v[204:207], v[48:51]
	v_mfma_f32_16x16x32_bf16 v[40:43], v[180:183], v[204:207], v[40:43]
	v_mfma_f32_16x16x32_bf16 v[32:35], v[172:175], v[212:215], v[32:35]
	v_mfma_f32_16x16x32_bf16 v[24:27], v[180:183], v[212:215], v[24:27]
	v_mfma_f32_16x16x32_bf16 v[16:19], v[172:175], v[220:223], v[16:19]
	v_mfma_f32_16x16x32_bf16 v[8:11], v[180:183], v[220:223], v[8:11]
	v_mfma_f32_16x16x32_bf16 v[72:75], v[176:179], v[200:203], v[72:75]
	v_mfma_f32_16x16x32_bf16 v[64:67], v[184:187], v[200:203], v[64:67]
	v_mfma_f32_16x16x32_bf16 v[48:51], v[176:179], v[208:211], v[48:51]
	v_mfma_f32_16x16x32_bf16 v[40:43], v[184:187], v[208:211], v[40:43]
	v_mfma_f32_16x16x32_bf16 v[32:35], v[176:179], v[216:219], v[32:35]
	v_mfma_f32_16x16x32_bf16 v[24:27], v[184:187], v[216:219], v[24:27]
	s_setprio 2
	s_barrier
	v_mfma_f32_16x16x32_bf16 v[16:19], v[176:179], v[224:227], v[16:19]
	v_mfma_f32_16x16x32_bf16 v[8:11], v[184:187], v[224:227], v[8:11]
	s_setprio 0
	s_add_i32 s78, s78, 2
	s_add_u32 s76, s76, 0x10000
	s_addc_u32 s77, s77, 0
	s_cmp_gt_u32 s78, 13
	s_mov_b64 s[18:19], s[40:41]
	s_cbranch_scc0 .LBB0_1093
	s_and_b64 vcc, exec, s[10:11]
	s_cbranch_vccz .LBB0_1096
	s_barrier

.LBB0_1249:
	s_add_u32 s11, s12, s6
	v_add_u32_e32 v160, s40, v150
	s_addc_u32 s18, s13, s7
	ds_read_b128 v[152:155], v160
	ds_read_b128 v[156:159], v160 offset:1024
	ds_read_b128 v[164:167], v160 offset:2048
	ds_read_b128 v[168:171], v160 offset:3072
	v_add_u32_e32 v160, s41, v150
	s_add_u32 s11, s11, 0x10000
	ds_read_b128 v[172:175], v160
	ds_read_b128 v[182:185], v160 offset:1024
	ds_read_b128 v[190:193], v160 offset:2048
	ds_read_b128 v[194:197], v160 offset:3072
	s_addc_u32 s18, s18, 0
	s_add_u32 s19, s49, s6
	s_addc_u32 s21, s50, s7
	s_cmp_eq_u32 s6, 0x150000
	s_cselect_b32 s22, s52, s11
	s_cselect_b32 s23, s51, s18
	s_cselect_b32 s20, s54, s19
	s_cselect_b32 s21, s53, s21
	s_add_u32 s18, s22, 0x8000
	s_addc_u32 s19, s23, 0
	s_add_i32 s11, s29, 0xc000
	v_lshl_add_u64 v[160:161], v[144:145], 0, s[6:7]
	s_mov_b32 m0, s11
	s_add_i32 s48, s29, 0xe000
	ds_read_b128 v[198:201], v151
	ds_read_b128 v[202:205], v151 offset:1024
	ds_read_b128 v[206:209], v151 offset:2048
	ds_read_b128 v[210:213], v151 offset:3072
	ds_read_b128 v[214:217], v151 offset:4096
	ds_read_b128 v[218:221], v151 offset:5120
	ds_read_b128 v[222:225], v151 offset:6144
	ds_read_b128 v[226:229], v151 offset:7168
	global_load_lds_dwordx4 v[160:161], off sc1
	v_lshl_add_u64 v[160:161], v[146:147], 0, s[6:7]
	s_mov_b32 m0, s48
	s_nop 0
	global_load_lds_dwordx4 v[160:161], off sc1
	s_waitcnt vmcnt(8)
	s_waitcnt lgkmcnt(0)
	s_setprio 1
	s_barrier
	v_mfma_f32_16x16x32_bf16 v[128:131], v[152:155], v[198:201], v[128:131]
	v_mfma_f32_16x16x32_bf16 v[132:135], v[164:167], v[198:201], v[132:135]
	v_mfma_f32_16x16x32_bf16 v[112:115], v[152:155], v[206:209], v[112:115]
	v_mfma_f32_16x16x32_bf16 v[116:119], v[164:167], v[206:209], v[116:119]
	v_mfma_f32_16x16x32_bf16 v[96:99], v[152:155], v[214:217], v[96:99]
	v_mfma_f32_16x16x32_bf16 v[100:103], v[164:167], v[214:217], v[100:103]
	v_mfma_f32_16x16x32_bf16 v[72:75], v[152:155], v[222:225], v[72:75]
	v_mfma_f32_16x16x32_bf16 v[76:79], v[164:167], v[222:225], v[76:79]
	v_mfma_f32_16x16x32_bf16 v[128:131], v[156:159], v[202:205], v[128:131]
	v_mfma_f32_16x16x32_bf16 v[132:135], v[168:171], v[202:205], v[132:135]
	v_mfma_f32_16x16x32_bf16 v[112:115], v[156:159], v[210:213], v[112:115]
	v_mfma_f32_16x16x32_bf16 v[116:119], v[168:171], v[210:213], v[116:119]
	v_mfma_f32_16x16x32_bf16 v[96:99], v[156:159], v[218:221], v[96:99]
	v_mfma_f32_16x16x32_bf16 v[100:103], v[168:171], v[218:221], v[100:103]
	v_mfma_f32_16x16x32_bf16 v[72:75], v[156:159], v[226:229], v[72:75]
	v_mfma_f32_16x16x32_bf16 v[76:79], v[168:171], v[226:229], v[76:79]
	v_mfma_f32_16x16x32_bf16 v[136:139], v[172:175], v[198:201], v[136:139]
	v_mfma_f32_16x16x32_bf16 v[140:143], v[190:193], v[198:201], v[140:143]
	v_mfma_f32_16x16x32_bf16 v[120:123], v[172:175], v[206:209], v[120:123]
	v_mfma_f32_16x16x32_bf16 v[124:127], v[190:193], v[206:209], v[124:127]
	v_mfma_f32_16x16x32_bf16 v[104:107], v[172:175], v[214:217], v[104:107]
	v_mfma_f32_16x16x32_bf16 v[108:111], v[190:193], v[214:217], v[108:111]
	v_mfma_f32_16x16x32_bf16 v[88:91], v[172:175], v[222:225], v[88:91]
	v_mfma_f32_16x16x32_bf16 v[92:95], v[190:193], v[222:225], v[92:95]
	v_mfma_f32_16x16x32_bf16 v[136:139], v[182:185], v[202:205], v[136:139]
	v_mfma_f32_16x16x32_bf16 v[140:143], v[194:197], v[202:205], v[140:143]
	v_mfma_f32_16x16x32_bf16 v[120:123], v[182:185], v[210:213], v[120:123]
	v_mfma_f32_16x16x32_bf16 v[124:127], v[194:197], v[210:213], v[124:127]
	v_mfma_f32_16x16x32_bf16 v[104:107], v[182:185], v[218:221], v[104:107]
	v_mfma_f32_16x16x32_bf16 v[108:111], v[194:197], v[218:221], v[108:111]
	s_setprio 2
	s_barrier
	v_mfma_f32_16x16x32_bf16 v[88:91], v[182:185], v[226:229], v[88:91]
	v_mfma_f32_16x16x32_bf16 v[92:95], v[194:197], v[226:229], v[92:95]
	s_setprio 0
	s_add_i32 s56, s40, s27
	s_mov_b32 m0, s56
	ds_read_b128 v[198:201], v151 offset:16384
	ds_read_b128 v[202:205], v151 offset:17408
	ds_read_b128 v[206:209], v151 offset:18432
	ds_read_b128 v[210:213], v151 offset:19456
	ds_read_b128 v[214:217], v151 offset:20480
	ds_read_b128 v[218:221], v151 offset:21504
	ds_read_b128 v[222:225], v151 offset:22528
	ds_read_b128 v[226:229], v151 offset:23552
	global_load_lds_dwordx4 v2, s[20:21] sc1
	s_add_i32 m0, s56, 0x2000
	s_add_u32 s56, s20, 0x4000
	s_addc_u32 s57, s21, 0
	s_add_i32 s58, s41, s27
	global_load_lds_dwordx4 v6, s[20:21] sc1
	s_mov_b32 m0, s58
	s_nop 0
	global_load_lds_dwordx4 v2, s[56:57] sc1
	s_add_i32 m0, s58, 0x2000
	s_nop 0
	global_load_lds_dwordx4 v6, s[56:57] sc1
	s_mov_b32 m0, s29
	s_nop 0
	global_load_lds_dwordx4 v0, s[22:23] sc1
	s_mov_b32 m0, s30
	s_nop 0
	global_load_lds_dwordx4 v4, s[22:23] sc1
	s_waitcnt vmcnt(8)
	s_waitcnt lgkmcnt(0)
	s_setprio 1
	s_barrier
	v_mfma_f32_16x16x32_bf16 v[64:67], v[152:155], v[198:201], v[64:67]
	v_mfma_f32_16x16x32_bf16 v[68:71], v[164:167], v[198:201], v[68:71]
	v_mfma_f32_16x16x32_bf16 v[48:51], v[152:155], v[206:209], v[48:51]
	v_mfma_f32_16x16x32_bf16 v[52:55], v[164:167], v[206:209], v[52:55]
	v_mfma_f32_16x16x32_bf16 v[32:35], v[152:155], v[214:217], v[32:35]
	v_mfma_f32_16x16x32_bf16 v[36:39], v[164:167], v[214:217], v[36:39]
	v_mfma_f32_16x16x32_bf16 v[16:19], v[152:155], v[222:225], v[16:19]
	v_mfma_f32_16x16x32_bf16 v[20:23], v[164:167], v[222:225], v[20:23]
	v_mfma_f32_16x16x32_bf16 v[64:67], v[156:159], v[202:205], v[64:67]
	v_mfma_f32_16x16x32_bf16 v[68:71], v[168:171], v[202:205], v[68:71]
	v_mfma_f32_16x16x32_bf16 v[48:51], v[156:159], v[210:213], v[48:51]
	v_mfma_f32_16x16x32_bf16 v[52:55], v[168:171], v[210:213], v[52:55]
	v_mfma_f32_16x16x32_bf16 v[32:35], v[156:159], v[218:221], v[32:35]
	v_mfma_f32_16x16x32_bf16 v[36:39], v[168:171], v[218:221], v[36:39]
	v_mfma_f32_16x16x32_bf16 v[16:19], v[156:159], v[226:229], v[16:19]
	v_mfma_f32_16x16x32_bf16 v[20:23], v[168:171], v[226:229], v[20:23]
	v_mfma_f32_16x16x32_bf16 v[80:83], v[172:175], v[198:201], v[80:83]
	v_mfma_f32_16x16x32_bf16 v[84:87], v[190:193], v[198:201], v[84:87]
	v_mfma_f32_16x16x32_bf16 v[56:59], v[172:175], v[206:209], v[56:59]
	v_mfma_f32_16x16x32_bf16 v[60:63], v[190:193], v[206:209], v[60:63]
	v_mfma_f32_16x16x32_bf16 v[40:43], v[172:175], v[214:217], v[40:43]
	v_mfma_f32_16x16x32_bf16 v[44:47], v[190:193], v[214:217], v[44:47]
	v_mfma_f32_16x16x32_bf16 v[24:27], v[172:175], v[222:225], v[24:27]
	v_mfma_f32_16x16x32_bf16 v[28:31], v[190:193], v[222:225], v[28:31]
	v_mfma_f32_16x16x32_bf16 v[80:83], v[182:185], v[202:205], v[80:83]
	v_mfma_f32_16x16x32_bf16 v[84:87], v[194:197], v[202:205], v[84:87]
	v_mfma_f32_16x16x32_bf16 v[56:59], v[182:185], v[210:213], v[56:59]
	v_mfma_f32_16x16x32_bf16 v[60:63], v[194:197], v[210:213], v[60:63]
	v_mfma_f32_16x16x32_bf16 v[40:43], v[182:185], v[218:221], v[40:43]
	v_mfma_f32_16x16x32_bf16 v[44:47], v[194:197], v[218:221], v[44:47]
	s_setprio 2
	s_barrier
	v_mfma_f32_16x16x32_bf16 v[24:27], v[182:185], v[226:229], v[24:27]
	v_mfma_f32_16x16x32_bf16 v[28:31], v[194:197], v[226:229], v[28:31]
	s_setprio 0
	v_add_u32_e32 v160, s43, v150
	ds_read_b128 v[152:155], v160
	ds_read_b128 v[156:159], v160 offset:1024
	ds_read_b128 v[164:167], v160 offset:2048
	ds_read_b128 v[168:171], v160 offset:3072
	v_add_u32_e32 v160, s44, v150
	ds_read_b128 v[172:175], v160
	ds_read_b128 v[182:185], v160 offset:1024
	ds_read_b128 v[190:193], v160 offset:2048
	ds_read_b128 v[194:197], v160 offset:3072
	s_add_u32 s22, s22, 0x4000
	s_addc_u32 s23, s23, 0
	s_mov_b32 m0, s31
	ds_read_b128 v[198:201], v151 offset:32768
	ds_read_b128 v[202:205], v151 offset:33792
	ds_read_b128 v[206:209], v151 offset:34816
	ds_read_b128 v[210:213], v151 offset:35840
	ds_read_b128 v[214:217], v151 offset:36864
	ds_read_b128 v[218:221], v151 offset:37888
	ds_read_b128 v[222:225], v151 offset:38912
	ds_read_b128 v[226:229], v151 offset:39936
	global_load_lds_dwordx4 v0, s[22:23] sc1
	s_mov_b32 m0, s35
	s_nop 0
	global_load_lds_dwordx4 v4, s[22:23] sc1
	s_waitcnt vmcnt(8)
	s_waitcnt lgkmcnt(0)
	s_setprio 1
	s_barrier
	v_mfma_f32_16x16x32_bf16 v[128:131], v[152:155], v[198:201], v[128:131]
	v_mfma_f32_16x16x32_bf16 v[132:135], v[164:167], v[198:201], v[132:135]
	v_mfma_f32_16x16x32_bf16 v[112:115], v[152:155], v[206:209], v[112:115]
	v_mfma_f32_16x16x32_bf16 v[116:119], v[164:167], v[206:209], v[116:119]
	v_mfma_f32_16x16x32_bf16 v[96:99], v[152:155], v[214:217], v[96:99]
	v_mfma_f32_16x16x32_bf16 v[100:103], v[164:167], v[214:217], v[100:103]
	v_mfma_f32_16x16x32_bf16 v[72:75], v[152:155], v[222:225], v[72:75]
	v_mfma_f32_16x16x32_bf16 v[76:79], v[164:167], v[222:225], v[76:79]
	v_mfma_f32_16x16x32_bf16 v[128:131], v[156:159], v[202:205], v[128:131]
	v_mfma_f32_16x16x32_bf16 v[132:135], v[168:171], v[202:205], v[132:135]
	v_mfma_f32_16x16x32_bf16 v[112:115], v[156:159], v[210:213], v[112:115]
	v_mfma_f32_16x16x32_bf16 v[116:119], v[168:171], v[210:213], v[116:119]
	v_mfma_f32_16x16x32_bf16 v[96:99], v[156:159], v[218:221], v[96:99]
	v_mfma_f32_16x16x32_bf16 v[100:103], v[168:171], v[218:221], v[100:103]
	v_mfma_f32_16x16x32_bf16 v[72:75], v[156:159], v[226:229], v[72:75]
	v_mfma_f32_16x16x32_bf16 v[76:79], v[168:171], v[226:229], v[76:79]
	v_mfma_f32_16x16x32_bf16 v[136:139], v[172:175], v[198:201], v[136:139]
	v_mfma_f32_16x16x32_bf16 v[140:143], v[190:193], v[198:201], v[140:143]
	v_mfma_f32_16x16x32_bf16 v[120:123], v[172:175], v[206:209], v[120:123]
	v_mfma_f32_16x16x32_bf16 v[124:127], v[190:193], v[206:209], v[124:127]
	v_mfma_f32_16x16x32_bf16 v[104:107], v[172:175], v[214:217], v[104:107]
	v_mfma_f32_16x16x32_bf16 v[108:111], v[190:193], v[214:217], v[108:111]
	v_mfma_f32_16x16x32_bf16 v[88:91], v[172:175], v[222:225], v[88:91]
	v_mfma_f32_16x16x32_bf16 v[92:95], v[190:193], v[222:225], v[92:95]
	v_mfma_f32_16x16x32_bf16 v[136:139], v[182:185], v[202:205], v[136:139]
	v_mfma_f32_16x16x32_bf16 v[140:143], v[194:197], v[202:205], v[140:143]
	v_mfma_f32_16x16x32_bf16 v[120:123], v[182:185], v[210:213], v[120:123]
	v_mfma_f32_16x16x32_bf16 v[124:127], v[194:197], v[210:213], v[124:127]
	v_mfma_f32_16x16x32_bf16 v[104:107], v[182:185], v[218:221], v[104:107]
	v_mfma_f32_16x16x32_bf16 v[108:111], v[194:197], v[218:221], v[108:111]
	s_setprio 2
	s_barrier
	v_mfma_f32_16x16x32_bf16 v[88:91], v[182:185], v[226:229], v[88:91]
	v_mfma_f32_16x16x32_bf16 v[92:95], v[194:197], v[226:229], v[92:95]
	s_setprio 0
	s_add_u32 s22, s20, 0x8000
	s_addc_u32 s23, s21, 0
	s_add_i32 s56, s43, s27
	s_mov_b32 m0, s56
	ds_read_b128 v[198:201], v151 offset:49152
	ds_read_b128 v[202:205], v151 offset:50176
	ds_read_b128 v[206:209], v151 offset:51200
	ds_read_b128 v[210:213], v151 offset:52224
	ds_read_b128 v[214:217], v151 offset:53248
	ds_read_b128 v[218:221], v151 offset:54272
	ds_read_b128 v[222:225], v151 offset:55296
	ds_read_b128 v[226:229], v151 offset:56320
	global_load_lds_dwordx4 v2, s[22:23] sc1
	s_add_i32 m0, s56, 0x2000
	s_add_u32 s20, s20, 0xc000
	global_load_lds_dwordx4 v6, s[22:23] sc1
	s_addc_u32 s21, s21, 0
	s_add_i32 s22, s44, s27
	s_mov_b32 m0, s22
	s_nop 0
	global_load_lds_dwordx4 v2, s[20:21] sc1
	s_add_i32 m0, s22, 0x2000
	s_nop 0
	global_load_lds_dwordx4 v6, s[20:21] sc1
	s_mov_b32 m0, s38
	s_nop 0
	global_load_lds_dwordx4 v0, s[18:19] sc1
	s_mov_b32 m0, s39
	s_nop 0
	global_load_lds_dwordx4 v4, s[18:19] sc1
	s_waitcnt vmcnt(8)
	s_waitcnt lgkmcnt(0)
	s_setprio 1
	s_barrier
	v_mfma_f32_16x16x32_bf16 v[64:67], v[152:155], v[198:201], v[64:67]
	v_mfma_f32_16x16x32_bf16 v[68:71], v[164:167], v[198:201], v[68:71]
	v_mfma_f32_16x16x32_bf16 v[48:51], v[152:155], v[206:209], v[48:51]
	v_mfma_f32_16x16x32_bf16 v[52:55], v[164:167], v[206:209], v[52:55]
	v_mfma_f32_16x16x32_bf16 v[32:35], v[152:155], v[214:217], v[32:35]
	v_mfma_f32_16x16x32_bf16 v[36:39], v[164:167], v[214:217], v[36:39]
	v_mfma_f32_16x16x32_bf16 v[16:19], v[152:155], v[222:225], v[16:19]
	v_mfma_f32_16x16x32_bf16 v[20:23], v[164:167], v[222:225], v[20:23]
	v_mfma_f32_16x16x32_bf16 v[64:67], v[156:159], v[202:205], v[64:67]
	v_mfma_f32_16x16x32_bf16 v[68:71], v[168:171], v[202:205], v[68:71]
	v_mfma_f32_16x16x32_bf16 v[48:51], v[156:159], v[210:213], v[48:51]
	v_mfma_f32_16x16x32_bf16 v[52:55], v[168:171], v[210:213], v[52:55]
	v_mfma_f32_16x16x32_bf16 v[32:35], v[156:159], v[218:221], v[32:35]
	v_mfma_f32_16x16x32_bf16 v[36:39], v[168:171], v[218:221], v[36:39]
	v_mfma_f32_16x16x32_bf16 v[16:19], v[156:159], v[226:229], v[16:19]
	v_mfma_f32_16x16x32_bf16 v[20:23], v[168:171], v[226:229], v[20:23]
	v_mfma_f32_16x16x32_bf16 v[80:83], v[172:175], v[198:201], v[80:83]
	v_mfma_f32_16x16x32_bf16 v[84:87], v[190:193], v[198:201], v[84:87]
	v_mfma_f32_16x16x32_bf16 v[56:59], v[172:175], v[206:209], v[56:59]
	v_mfma_f32_16x16x32_bf16 v[60:63], v[190:193], v[206:209], v[60:63]
	v_mfma_f32_16x16x32_bf16 v[40:43], v[172:175], v[214:217], v[40:43]
	v_mfma_f32_16x16x32_bf16 v[44:47], v[190:193], v[214:217], v[44:47]
	v_mfma_f32_16x16x32_bf16 v[24:27], v[172:175], v[222:225], v[24:27]
	v_mfma_f32_16x16x32_bf16 v[28:31], v[190:193], v[222:225], v[28:31]
	v_mfma_f32_16x16x32_bf16 v[80:83], v[182:185], v[202:205], v[80:83]
	v_mfma_f32_16x16x32_bf16 v[84:87], v[194:197], v[202:205], v[84:87]
	v_mfma_f32_16x16x32_bf16 v[56:59], v[182:185], v[210:213], v[56:59]
	v_mfma_f32_16x16x32_bf16 v[60:63], v[194:197], v[210:213], v[60:63]
	v_mfma_f32_16x16x32_bf16 v[40:43], v[182:185], v[218:221], v[40:43]
	v_mfma_f32_16x16x32_bf16 v[44:47], v[194:197], v[218:221], v[44:47]
	s_setprio 2
	s_barrier
	v_mfma_f32_16x16x32_bf16 v[24:27], v[182:185], v[226:229], v[24:27]
	v_mfma_f32_16x16x32_bf16 v[28:31], v[194:197], v[226:229], v[28:31]
	s_setprio 0
	s_add_i32 s55, s55, 2
	s_add_u32 s6, s6, 0x10000
	s_addc_u32 s7, s7, 0
	s_cmp_gt_u32 s55, 41
	s_cbranch_scc0 .LBB0_1249
	s_add_u32 s6, s49, 0xffff0000
	s_addc_u32 s7, s50, -1
	s_and_b64 vcc, exec, s[4:5]
	s_cbranch_vccnz .LBB0_1236
	s_mov_b32 s8, s45
	s_mov_b32 s10, s46
	s_mov_b64 s[12:13], s[16:17]
	s_mov_b32 s42, s47
	v_mov_b64 v[128:129], 0
	v_mov_b64 v[130:131], 0
	v_mov_b64 v[132:133], 0
	v_mov_b64 v[134:135], 0
	v_mov_b64 v[112:113], 0
	v_mov_b64 v[114:115], 0
	v_mov_b64 v[116:117], 0
	v_mov_b64 v[118:119], 0
	v_mov_b64 v[96:97], 0
	v_mov_b64 v[98:99], 0
	v_mov_b64 v[100:101], 0
	v_mov_b64 v[102:103], 0
	v_mov_b64 v[72:73], 0
	v_mov_b64 v[74:75], 0
	v_mov_b64 v[76:77], 0
	v_mov_b64 v[78:79], 0
	v_mov_b64 v[136:137], 0
	v_mov_b64 v[138:139], 0
	v_mov_b64 v[140:141], 0
	v_mov_b64 v[142:143], 0
	v_mov_b64 v[120:121], 0
	v_mov_b64 v[122:123], 0
	v_mov_b64 v[124:125], 0
	v_mov_b64 v[126:127], 0
	v_mov_b64 v[104:105], 0
	v_mov_b64 v[106:107], 0
	v_mov_b64 v[108:109], 0
	v_mov_b64 v[110:111], 0
	v_mov_b64 v[88:89], 0
	v_mov_b64 v[90:91], 0
	v_mov_b64 v[92:93], 0
	v_mov_b64 v[94:95], 0
	v_mov_b64 v[64:65], 0
	v_mov_b64 v[66:67], 0
	v_mov_b64 v[68:69], 0
	v_mov_b64 v[70:71], 0
	v_mov_b64 v[48:49], 0
	v_mov_b64 v[50:51], 0
	v_mov_b64 v[52:53], 0
	v_mov_b64 v[54:55], 0
	v_mov_b64 v[32:33], 0
	v_mov_b64 v[34:35], 0
	v_mov_b64 v[36:37], 0
	v_mov_b64 v[38:39], 0
	v_mov_b64 v[16:17], 0
	v_mov_b64 v[18:19], 0
	v_mov_b64 v[20:21], 0
	v_mov_b64 v[22:23], 0
	v_mov_b64 v[80:81], 0
	v_mov_b64 v[82:83], 0
	v_mov_b64 v[84:85], 0
	v_mov_b64 v[86:87], 0
	v_mov_b64 v[56:57], 0
	v_mov_b64 v[58:59], 0
	v_mov_b64 v[60:61], 0
	v_mov_b64 v[62:63], 0
	v_mov_b64 v[40:41], 0
	v_mov_b64 v[42:43], 0
	v_mov_b64 v[44:45], 0
	v_mov_b64 v[46:47], 0
	v_mov_b64 v[24:25], 0
	v_mov_b64 v[26:27], 0
	v_mov_b64 v[28:29], 0
	v_mov_b64 v[30:31], 0
	s_andn2_b64 vcc, exec, s[0:1]
	s_cbranch_vccnz .LBB0_1237
